# peeled first K iteration of SwiGLU loop with C=0, removed redundant post-barrier lgkmcnt waits in MFMA sections, unit-order division by 8 as shift
# speedup vs baseline: 1.0225x; 1.0076x over previous
;     __host__ __device__ bool next(int i, Unit& u) const {
;         const long L = (long)i * G + c; if (L >= nwg) return false;
;         int wgid = (int)L; { const int q = nwg / NXCD, r = nwg % NXCD, xcd = wgid % NXCD, off = wgid / NXCD; wgid = (xcd < r ? xcd * (q + 1) : r * (q + 1) + (xcd - r) * q) + off; }
;         const int nig = WGM * nN, gid = wgid / nig, fm = gid * WGM, gsz = (nM - fm) < WGM ? (nM - fm) : WGM;
;         u.pm = fm + ((wgid % nig) % gsz); u.pn = (wgid % nig) / gsz; return true;
;     }
.LBB0_222:
	s_add_i32 s44, s44, 1
	s_mul_i32 s4, s44, s89
	s_mul_hi_u32 s5, s44, s88
	s_add_i32 s5, s5, s4
	s_mul_i32 s4, s44, s88
	s_add_u32 s12, s4, s86
	s_addc_u32 s13, s5, s95
	v_mov_b64_e32 v[0:1], 0x500
	v_cmp_lt_i64_e64 s[4:5], s[12:13], v[0:1]
	v_mov_b64_e32 v[0:1], 0x4ff
	v_cmp_gt_i64_e32 vcc, s[12:13], v[0:1]
	s_cbranch_vccnz .LBB0_224
	s_ashr_i32 s8, s12, 31
	s_lshr_b32 s8, s8, 29
	s_add_i32 s8, s12, s8
	s_ashr_i32 s9, s8, 3
	s_and_b32 s8, s8, -8
	s_sub_i32 s8, s12, s8
	s_cmp_lt_i32 s8, 0
	s_movk_i32 s10, 0xa1
	s_cselect_b32 s10, s10, 0xa0
	s_mul_i32 s8, s8, s10
	s_add_i32 s8, s8, s9
	s_mul_hi_i32 s9, s8, 0x66666667
	s_lshr_b32 s10, s9, 31
	s_ashr_i32 s9, s9, 4
	s_add_i32 s9, s9, s10
	s_lshl_b32 s10, s9, 3
	s_sub_i32 s11, 0x100, s10
	s_min_i32 s11, s11, 8
	s_mul_i32 s9, s9, 40
	s_sub_i32 s9, s8, s9
	s_lshr_b32 s8, s9, 3
	s_and_b32 s9, s9, 7
	s_add_i32 s10, s10, s9

; #define PG8_STAGE(bufoff, gbase, voff) do { _Pragma("unroll") for (int _i = 0; _i < 2; ++_i) \
;         __builtin_amdgcn_global_load_lds((const unsigned*)((const char*)(gbase) + (voff)[_i]), (LAS unsigned*)(lds + (bufoff) + ldsw + _i * 8192), 16, 0, 0); } while (0)
; #define PG8_LDA(dst, b, h) do { _Pragma("unroll") for (int m = 0; m < 4; ++m) _Pragma("unroll") for (int k = 0; k < 2; ++k) dst[m][k] = *(const LAS bf16x8*)(lds + PG8_SA(b, h) + aoff + m * 2048 + k * 1024); } while (0)
; #define PG8_LDB(dst, b, h) do { _Pragma("unroll") for (int n = 0; n < 2; ++n) _Pragma("unroll") for (int k = 0; k < 2; ++k) dst[n][k] = *(const LAS bf16x8*)(lds + PG8_SB(b, h) + boff + n * 2048 + k * 1024); } while (0)
; #define PG8_MMA(ai, bj, At, Bt) do { __builtin_amdgcn_s_setprio(1); _Pragma("unroll") for (int m = 0; m < 4; ++m) _Pragma("unroll") for (int n = 0; n < 2; ++n) _Pragma("unroll") for (int k = 0; k < 2; ++k) \
;         acc[ai][bj][m][n] = __builtin_amdgcn_mfma_f32_16x16x32_bf16(Bt[n][k], At[m][k], acc[ai][bj][m][n], 0, 0, 0); __builtin_amdgcn_s_setprio(0); } while (0)
; #define PG8_WAIT_V(n) asm volatile("s_waitcnt vmcnt(" #n ")" ::: "memory")
; template <class Epi>
; __device__ __forceinline__ void gemm_phase(LAS unsigned char* lds, const Gemm g, const StaticOrder& S, const Epi& E, const int tid) {
;     ...
;             PG8_LDB(B0, 0, 0); PG8_LDB(B1, 0, 1); PG8_SCHED; PG8_LDA(At, 0, 0); PG8_STAGE(PG8_SA(1, 1), a1 + hstepA, voffA);
;             PG8_WAIT_V(8); PG8_WAIT_L(0); PG8_BAR; PG8_MMA(0, 0, At, B0); PG8_MMA(0, 1, At, B1); PG8_BAR; PG8_SCHED;
;             PG8_LDA(At, 0, 1); PG8_STAGE(PG8_SB(0, 0), b2, voffB); PG8_STAGE(PG8_SB(0, 1), b2 + hstepB, voffB); PG8_STAGE(PG8_SA(0, 0), a2, voffA);
;             PG8_WAIT_V(8); PG8_WAIT_L(0); PG8_BAR; PG8_MMA(1, 0, At, B0); PG8_MMA(1, 1, At, B1); PG8_BAR; PG8_SCHED;
;             PG8_LDB(B0, 1, 0); PG8_LDB(B1, 1, 1); PG8_SCHED; PG8_LDA(At, 1, 0); PG8_STAGE(PG8_SA(0, 1), a2 + hstepA, voffA);
;             PG8_WAIT_V(8); PG8_WAIT_L(0); PG8_BAR; PG8_MMA(0, 0, At, B0); PG8_MMA(0, 1, At, B1); PG8_BAR; PG8_SCHED;
;             PG8_LDA(At, 1, 1); PG8_STAGE(PG8_SB(1, 0), b3, voffB); PG8_STAGE(PG8_SB(1, 1), b3 + hstepB, voffB); PG8_STAGE(PG8_SA(1, 0), a3, voffA);
;             PG8_WAIT_V(8); PG8_WAIT_L(0); PG8_BAR; PG8_MMA(1, 0, At, B0); PG8_MMA(1, 1, At, B1); PG8_BAR; PG8_SCHED;
;         }
.LBB0_225:
	s_add_u32 s28, s16, 0x1000
	s_addc_u32 s29, s17, 0
	s_add_i32 s52, 0, 0x10000
	s_cmp_eq_u32 s51, 12
	s_cselect_b32 s41, s11, s29
	s_cselect_b32 s40, s47, s28
	s_cselect_b32 s35, s9, s50
	s_cselect_b32 s34, s48, s49
	s_add_i32 s53, 0, 0x14000
	v_add_u32_e32 v140, s52, v175
	v_add_u32_e32 v164, s53, v175
	ds_read_b128 v[128:131], v140
	ds_read_b128 v[132:135], v140 offset:1024
	ds_read_b128 v[136:139], v140 offset:2048
	ds_read_b128 v[140:143], v140 offset:3072
	ds_read_b128 v[156:159], v164
	ds_read_b128 v[160:163], v164 offset:1024
	ds_read_b128 v[168:171], v164 offset:2048
	ds_read_b128 v[178:181], v164 offset:3072
	v_lshl_add_u64 v[164:165], s[16:17], 0, v[152:153]
	s_add_i32 m0, s21, 0xc000
	ds_read_b128 v[202:205], v196
	ds_read_b128 v[206:209], v196 offset:1024
	ds_read_b128 v[210:213], v196 offset:2048
	ds_read_b128 v[214:217], v196 offset:3072
	ds_read_b128 v[226:229], v196 offset:4096
	ds_read_b128 v[230:233], v196 offset:5120
	ds_read_b128 v[234:237], v196 offset:6144
	ds_read_b128 v[238:241], v196 offset:7168
	global_load_lds_dwordx4 v[164:165], off
	v_lshl_add_u64 v[164:165], s[16:17], 0, v[154:155]
	s_add_i32 m0, s21, 0xe000
	s_nop 0
	global_load_lds_dwordx4 v[164:165], off
	s_waitcnt vmcnt(8)
	s_waitcnt lgkmcnt(0)
	s_barrier
	s_setprio 1
	v_mfma_f32_16x16x32_bf16 v[124:127], v[128:131], v[202:205], v[124:127]
	v_mfma_f32_16x16x32_bf16 v[120:123], v[136:139], v[202:205], v[120:123]
	v_mfma_f32_16x16x32_bf16 v[116:119], v[128:131], v[210:213], v[116:119]
	v_mfma_f32_16x16x32_bf16 v[108:111], v[136:139], v[210:213], v[108:111]
	v_mfma_f32_16x16x32_bf16 v[100:103], v[128:131], v[226:229], v[100:103]
	v_mfma_f32_16x16x32_bf16 v[92:95], v[136:139], v[226:229], v[92:95]
	v_mfma_f32_16x16x32_bf16 v[84:87], v[128:131], v[234:237], v[84:87]
	v_mfma_f32_16x16x32_bf16 v[76:79], v[136:139], v[234:237], v[76:79]
	v_mfma_f32_16x16x32_bf16 v[124:127], v[132:135], v[206:209], v[124:127]
	v_mfma_f32_16x16x32_bf16 v[120:123], v[140:143], v[206:209], v[120:123]
	v_mfma_f32_16x16x32_bf16 v[116:119], v[132:135], v[214:217], v[116:119]
	v_mfma_f32_16x16x32_bf16 v[108:111], v[140:143], v[214:217], v[108:111]
	v_mfma_f32_16x16x32_bf16 v[100:103], v[132:135], v[230:233], v[100:103]
	v_mfma_f32_16x16x32_bf16 v[92:95], v[140:143], v[230:233], v[92:95]
	v_mfma_f32_16x16x32_bf16 v[84:87], v[132:135], v[238:241], v[84:87]
	v_mfma_f32_16x16x32_bf16 v[76:79], v[140:143], v[238:241], v[76:79]
	s_setprio 0
	s_setprio 1
	v_mfma_f32_16x16x32_bf16 v[112:115], v[156:159], v[202:205], v[112:115]
	v_mfma_f32_16x16x32_bf16 v[104:107], v[168:171], v[202:205], v[104:107]
	v_mfma_f32_16x16x32_bf16 v[96:99], v[156:159], v[210:213], v[96:99]
	v_mfma_f32_16x16x32_bf16 v[88:91], v[168:171], v[210:213], v[88:91]
	v_mfma_f32_16x16x32_bf16 v[80:83], v[156:159], v[226:229], v[80:83]
	v_mfma_f32_16x16x32_bf16 v[72:75], v[168:171], v[226:229], v[72:75]
	v_mfma_f32_16x16x32_bf16 v[68:71], v[156:159], v[234:237], v[68:71]
	v_mfma_f32_16x16x32_bf16 v[64:67], v[168:171], v[234:237], v[64:67]
	v_mfma_f32_16x16x32_bf16 v[112:115], v[160:163], v[206:209], v[112:115]
	v_mfma_f32_16x16x32_bf16 v[104:107], v[178:181], v[206:209], v[104:107]
	v_mfma_f32_16x16x32_bf16 v[96:99], v[160:163], v[214:217], v[96:99]
	v_mfma_f32_16x16x32_bf16 v[88:91], v[178:181], v[214:217], v[88:91]
	v_mfma_f32_16x16x32_bf16 v[80:83], v[160:163], v[230:233], v[80:83]
	v_mfma_f32_16x16x32_bf16 v[72:75], v[178:181], v[230:233], v[72:75]
	v_mfma_f32_16x16x32_bf16 v[68:71], v[160:163], v[238:241], v[68:71]
	v_mfma_f32_16x16x32_bf16 v[64:67], v[178:181], v[238:241], v[64:67]
	s_setprio 0
	s_barrier
	s_add_i32 s16, s52, s20
	v_lshl_add_u64 v[164:165], s[34:35], 0, v[176:177]
	s_mov_b32 m0, s16
	ds_read_b128 v[202:205], v196 offset:16384
	ds_read_b128 v[206:209], v196 offset:17408
	ds_read_b128 v[210:213], v196 offset:18432
	ds_read_b128 v[214:217], v196 offset:19456
	ds_read_b128 v[226:229], v196 offset:20480
	ds_read_b128 v[230:233], v196 offset:21504
	ds_read_b128 v[234:237], v196 offset:22528
	ds_read_b128 v[238:241], v196 offset:23552
	global_load_lds_dwordx4 v[164:165], off
	s_add_i32 m0, s16, 0x2000
	s_add_u32 s16, s34, 0x40000
	v_lshl_add_u64 v[172:173], s[34:35], 0, v[144:145]
	s_addc_u32 s17, s35, 0
	s_add_i32 s52, s53, s20
	global_load_lds_dwordx4 v[172:173], off
	v_lshl_add_u64 v[194:195], s[16:17], 0, v[176:177]
	s_mov_b32 m0, s52
	v_lshl_add_u64 v[198:199], s[40:41], 0, v[146:147]
	global_load_lds_dwordx4 v[194:195], off
	v_lshl_add_u64 v[194:195], s[16:17], 0, v[144:145]
	s_add_i32 m0, s52, 0x2000
	s_nop 0
	global_load_lds_dwordx4 v[194:195], off
	v_lshl_add_u64 v[194:195], s[40:41], 0, v[148:149]
	s_mov_b32 m0, s21
	s_nop 0
	global_load_lds_dwordx4 v[194:195], off
	s_mov_b32 m0, s22
	s_nop 0
	global_load_lds_dwordx4 v[198:199], off
	s_waitcnt vmcnt(8)
	s_waitcnt lgkmcnt(0)
	s_barrier
; #define PG8_STAGE(bufoff, gbase, voff) do { _Pragma("unroll") for (int _i = 0; _i < 2; ++_i) \
;         __builtin_amdgcn_global_load_lds((const unsigned*)((const char*)(gbase) + (voff)[_i]), (LAS unsigned*)(lds + (bufoff) + ldsw + _i * 8192), 16, 0, 0); } while (0)
; #define PG8_LDA(dst, b, h) do { _Pragma("unroll") for (int m = 0; m < 4; ++m) _Pragma("unroll") for (int k = 0; k < 2; ++k) dst[m][k] = *(const LAS bf16x8*)(lds + PG8_SA(b, h) + aoff + m * 2048 + k * 1024); } while (0)
; #define PG8_LDB(dst, b, h) do { _Pragma("unroll") for (int n = 0; n < 2; ++n) _Pragma("unroll") for (int k = 0; k < 2; ++k) dst[n][k] = *(const LAS bf16x8*)(lds + PG8_SB(b, h) + boff + n * 2048 + k * 1024); } while (0)
; #define PG8_MMA(ai, bj, At, Bt) do { __builtin_amdgcn_s_setprio(1); _Pragma("unroll") for (int m = 0; m < 4; ++m) _Pragma("unroll") for (int n = 0; n < 2; ++n) _Pragma("unroll") for (int k = 0; k < 2; ++k) \
;         acc[ai][bj][m][n] = __builtin_amdgcn_mfma_f32_16x16x32_bf16(Bt[n][k], At[m][k], acc[ai][bj][m][n], 0, 0, 0); __builtin_amdgcn_s_setprio(0); } while (0)
; #define PG8_WAIT_V(n) asm volatile("s_waitcnt vmcnt(" #n ")" ::: "memory")
; template <class Epi>
; __device__ __forceinline__ void gemm_phase(LAS unsigned char* lds, const Gemm g, const StaticOrder& S, const Epi& E, const int tid) {
;     ...
;             PG8_LDB(B0, 0, 0); PG8_LDB(B1, 0, 1); PG8_SCHED; PG8_LDA(At, 0, 0); PG8_STAGE(PG8_SA(1, 1), a1 + hstepA, voffA);
;             PG8_WAIT_V(8); PG8_WAIT_L(0); PG8_BAR; PG8_MMA(0, 0, At, B0); PG8_MMA(0, 1, At, B1); PG8_BAR; PG8_SCHED;
;             PG8_LDA(At, 0, 1); PG8_STAGE(PG8_SB(0, 0), b2, voffB); PG8_STAGE(PG8_SB(0, 1), b2 + hstepB, voffB); PG8_STAGE(PG8_SA(0, 0), a2, voffA);
;             PG8_WAIT_V(8); PG8_WAIT_L(0); PG8_BAR; PG8_MMA(1, 0, At, B0); PG8_MMA(1, 1, At, B1); PG8_BAR; PG8_SCHED;
;             PG8_LDB(B0, 1, 0); PG8_LDB(B1, 1, 1); PG8_SCHED; PG8_LDA(At, 1, 0); PG8_STAGE(PG8_SA(0, 1), a2 + hstepA, voffA);
;             PG8_WAIT_V(8); PG8_WAIT_L(0); PG8_BAR; PG8_MMA(0, 0, At, B0); PG8_MMA(0, 1, At, B1); PG8_BAR; PG8_SCHED;
;             PG8_LDA(At, 1, 1); PG8_STAGE(PG8_SB(1, 0), b3, voffB); PG8_STAGE(PG8_SB(1, 1), b3 + hstepB, voffB); PG8_STAGE(PG8_SA(1, 0), a3, voffA);
;             PG8_WAIT_V(8); PG8_WAIT_L(0); PG8_BAR; PG8_MMA(1, 0, At, B0); PG8_MMA(1, 1, At, B1); PG8_BAR; PG8_SCHED;
;         }
	s_setprio 1
	v_mfma_f32_16x16x32_bf16 v[60:63], v[128:131], v[202:205], v[60:63]
	v_mfma_f32_16x16x32_bf16 v[56:59], v[136:139], v[202:205], v[56:59]
	v_mfma_f32_16x16x32_bf16 v[52:55], v[128:131], v[210:213], v[52:55]
	v_mfma_f32_16x16x32_bf16 v[44:47], v[136:139], v[210:213], v[44:47]
	v_mfma_f32_16x16x32_bf16 v[36:39], v[128:131], v[226:229], v[36:39]
	v_mfma_f32_16x16x32_bf16 v[28:31], v[136:139], v[226:229], v[28:31]
	v_mfma_f32_16x16x32_bf16 v[20:23], v[128:131], v[234:237], v[20:23]
	v_mfma_f32_16x16x32_bf16 v[12:15], v[136:139], v[234:237], v[12:15]
	v_mfma_f32_16x16x32_bf16 v[60:63], v[132:135], v[206:209], v[60:63]
	v_mfma_f32_16x16x32_bf16 v[56:59], v[140:143], v[206:209], v[56:59]
	v_mfma_f32_16x16x32_bf16 v[52:55], v[132:135], v[214:217], v[52:55]
	v_mfma_f32_16x16x32_bf16 v[44:47], v[140:143], v[214:217], v[44:47]
	v_mfma_f32_16x16x32_bf16 v[36:39], v[132:135], v[230:233], v[36:39]
	v_mfma_f32_16x16x32_bf16 v[28:31], v[140:143], v[230:233], v[28:31]
	v_mfma_f32_16x16x32_bf16 v[20:23], v[132:135], v[238:241], v[20:23]
	v_mfma_f32_16x16x32_bf16 v[12:15], v[140:143], v[238:241], v[12:15]
	s_setprio 0
	s_setprio 1
	v_mfma_f32_16x16x32_bf16 v[48:51], v[156:159], v[202:205], v[48:51]
	v_mfma_f32_16x16x32_bf16 v[40:43], v[168:171], v[202:205], v[40:43]
	v_mfma_f32_16x16x32_bf16 v[32:35], v[156:159], v[210:213], v[32:35]
	v_mfma_f32_16x16x32_bf16 v[24:27], v[168:171], v[210:213], v[24:27]
	v_mfma_f32_16x16x32_bf16 v[16:19], v[156:159], v[226:229], v[16:19]
	v_mfma_f32_16x16x32_bf16 v[8:11], v[168:171], v[226:229], v[8:11]
	v_mfma_f32_16x16x32_bf16 v[4:7], v[156:159], v[234:237], v[4:7]
	v_mfma_f32_16x16x32_bf16 v[0:3], v[168:171], v[234:237], v[0:3]
	v_mfma_f32_16x16x32_bf16 v[48:51], v[160:163], v[206:209], v[48:51]
	v_mfma_f32_16x16x32_bf16 v[40:43], v[178:181], v[206:209], v[40:43]
	v_mfma_f32_16x16x32_bf16 v[32:35], v[160:163], v[214:217], v[32:35]
	v_mfma_f32_16x16x32_bf16 v[24:27], v[178:181], v[214:217], v[24:27]
	v_mfma_f32_16x16x32_bf16 v[16:19], v[160:163], v[230:233], v[16:19]
	v_mfma_f32_16x16x32_bf16 v[8:11], v[178:181], v[230:233], v[8:11]
	v_mfma_f32_16x16x32_bf16 v[4:7], v[160:163], v[238:241], v[4:7]
	v_mfma_f32_16x16x32_bf16 v[0:3], v[178:181], v[238:241], v[0:3]
	s_setprio 0
	s_barrier
	s_add_i32 s52, 0, 0x18000
	s_add_i32 s53, 0, 0x1c000
	v_add_u32_e32 v140, s52, v175
	v_add_u32_e32 v166, s53, v175
	ds_read_b128 v[128:131], v140
	ds_read_b128 v[132:135], v140 offset:1024
	ds_read_b128 v[136:139], v140 offset:2048
	ds_read_b128 v[140:143], v140 offset:3072
	ds_read_b128 v[156:159], v166
	ds_read_b128 v[160:163], v166 offset:1024
	ds_read_b128 v[168:171], v166 offset:2048
	ds_read_b128 v[178:181], v166 offset:3072
	s_add_u32 s16, s40, 0x40000
	s_addc_u32 s17, s41, 0
	s_mov_b32 m0, s23
	v_lshl_add_u64 v[218:219], s[16:17], 0, v[148:149]
	ds_read_b128 v[202:205], v196 offset:32768
	ds_read_b128 v[206:209], v196 offset:33792
	ds_read_b128 v[210:213], v196 offset:34816
	ds_read_b128 v[214:217], v196 offset:35840
	ds_read_b128 v[226:229], v196 offset:36864
	ds_read_b128 v[230:233], v196 offset:37888
	ds_read_b128 v[234:237], v196 offset:38912
	ds_read_b128 v[238:241], v196 offset:39936
	global_load_lds_dwordx4 v[218:219], off
	v_lshl_add_u64 v[218:219], s[16:17], 0, v[146:147]
	s_mov_b32 m0, s30
	s_nop 0
	global_load_lds_dwordx4 v[218:219], off
	s_waitcnt vmcnt(8)
	s_waitcnt lgkmcnt(0)
	s_barrier
	s_setprio 1
	v_mfma_f32_16x16x32_bf16 v[124:127], v[128:131], v[202:205], v[124:127]
	v_mfma_f32_16x16x32_bf16 v[120:123], v[136:139], v[202:205], v[120:123]
	v_mfma_f32_16x16x32_bf16 v[116:119], v[128:131], v[210:213], v[116:119]
	v_mfma_f32_16x16x32_bf16 v[108:111], v[136:139], v[210:213], v[108:111]
	v_mfma_f32_16x16x32_bf16 v[100:103], v[128:131], v[226:229], v[100:103]
	v_mfma_f32_16x16x32_bf16 v[92:95], v[136:139], v[226:229], v[92:95]
	v_mfma_f32_16x16x32_bf16 v[84:87], v[128:131], v[234:237], v[84:87]
	v_mfma_f32_16x16x32_bf16 v[76:79], v[136:139], v[234:237], v[76:79]
	v_mfma_f32_16x16x32_bf16 v[124:127], v[132:135], v[206:209], v[124:127]
	v_mfma_f32_16x16x32_bf16 v[120:123], v[140:143], v[206:209], v[120:123]
	v_mfma_f32_16x16x32_bf16 v[116:119], v[132:135], v[214:217], v[116:119]
	v_mfma_f32_16x16x32_bf16 v[108:111], v[140:143], v[214:217], v[108:111]
	v_mfma_f32_16x16x32_bf16 v[100:103], v[132:135], v[230:233], v[100:103]
	v_mfma_f32_16x16x32_bf16 v[92:95], v[140:143], v[230:233], v[92:95]
	v_mfma_f32_16x16x32_bf16 v[84:87], v[132:135], v[238:241], v[84:87]
	v_mfma_f32_16x16x32_bf16 v[76:79], v[140:143], v[238:241], v[76:79]
	s_setprio 0
	s_setprio 1
	v_mfma_f32_16x16x32_bf16 v[112:115], v[156:159], v[202:205], v[112:115]
	v_mfma_f32_16x16x32_bf16 v[104:107], v[168:171], v[202:205], v[104:107]
	v_mfma_f32_16x16x32_bf16 v[96:99], v[156:159], v[210:213], v[96:99]
	v_mfma_f32_16x16x32_bf16 v[88:91], v[168:171], v[210:213], v[88:91]
	v_mfma_f32_16x16x32_bf16 v[80:83], v[156:159], v[226:229], v[80:83]
	v_mfma_f32_16x16x32_bf16 v[72:75], v[168:171], v[226:229], v[72:75]
	v_mfma_f32_16x16x32_bf16 v[68:71], v[156:159], v[234:237], v[68:71]
	v_mfma_f32_16x16x32_bf16 v[64:67], v[168:171], v[234:237], v[64:67]
	v_mfma_f32_16x16x32_bf16 v[112:115], v[160:163], v[206:209], v[112:115]
	v_mfma_f32_16x16x32_bf16 v[104:107], v[178:181], v[206:209], v[104:107]
	v_mfma_f32_16x16x32_bf16 v[96:99], v[160:163], v[214:217], v[96:99]
	v_mfma_f32_16x16x32_bf16 v[88:91], v[178:181], v[214:217], v[88:91]
	v_mfma_f32_16x16x32_bf16 v[80:83], v[160:163], v[230:233], v[80:83]
	v_mfma_f32_16x16x32_bf16 v[72:75], v[178:181], v[230:233], v[72:75]
	v_mfma_f32_16x16x32_bf16 v[68:71], v[160:163], v[238:241], v[68:71]
	v_mfma_f32_16x16x32_bf16 v[64:67], v[178:181], v[238:241], v[64:67]
	s_setprio 0
	s_barrier
; #define PG8_STAGE(bufoff, gbase, voff) do { _Pragma("unroll") for (int _i = 0; _i < 2; ++_i) \
;         __builtin_amdgcn_global_load_lds((const unsigned*)((const char*)(gbase) + (voff)[_i]), (LAS unsigned*)(lds + (bufoff) + ldsw + _i * 8192), 16, 0, 0); } while (0)
; #define PG8_LDA(dst, b, h) do { _Pragma("unroll") for (int m = 0; m < 4; ++m) _Pragma("unroll") for (int k = 0; k < 2; ++k) dst[m][k] = *(const LAS bf16x8*)(lds + PG8_SA(b, h) + aoff + m * 2048 + k * 1024); } while (0)
; #define PG8_LDB(dst, b, h) do { _Pragma("unroll") for (int n = 0; n < 2; ++n) _Pragma("unroll") for (int k = 0; k < 2; ++k) dst[n][k] = *(const LAS bf16x8*)(lds + PG8_SB(b, h) + boff + n * 2048 + k * 1024); } while (0)
; #define PG8_MMA(ai, bj, At, Bt) do { __builtin_amdgcn_s_setprio(1); _Pragma("unroll") for (int m = 0; m < 4; ++m) _Pragma("unroll") for (int n = 0; n < 2; ++n) _Pragma("unroll") for (int k = 0; k < 2; ++k) \
;         acc[ai][bj][m][n] = __builtin_amdgcn_mfma_f32_16x16x32_bf16(Bt[n][k], At[m][k], acc[ai][bj][m][n], 0, 0, 0); __builtin_amdgcn_s_setprio(0); } while (0)
; #define PG8_WAIT_V(n) asm volatile("s_waitcnt vmcnt(" #n ")" ::: "memory")
; template <class Epi>
; __device__ __forceinline__ void gemm_phase(LAS unsigned char* lds, const Gemm g, const StaticOrder& S, const Epi& E, const int tid) {
;     ...
;             PG8_LDB(B0, 0, 0); PG8_LDB(B1, 0, 1); PG8_SCHED; PG8_LDA(At, 0, 0); PG8_STAGE(PG8_SA(1, 1), a1 + hstepA, voffA);
;             PG8_WAIT_V(8); PG8_WAIT_L(0); PG8_BAR; PG8_MMA(0, 0, At, B0); PG8_MMA(0, 1, At, B1); PG8_BAR; PG8_SCHED;
;             PG8_LDA(At, 0, 1); PG8_STAGE(PG8_SB(0, 0), b2, voffB); PG8_STAGE(PG8_SB(0, 1), b2 + hstepB, voffB); PG8_STAGE(PG8_SA(0, 0), a2, voffA);
;             PG8_WAIT_V(8); PG8_WAIT_L(0); PG8_BAR; PG8_MMA(1, 0, At, B0); PG8_MMA(1, 1, At, B1); PG8_BAR; PG8_SCHED;
;             PG8_LDB(B0, 1, 0); PG8_LDB(B1, 1, 1); PG8_SCHED; PG8_LDA(At, 1, 0); PG8_STAGE(PG8_SA(0, 1), a2 + hstepA, voffA);
;             PG8_WAIT_V(8); PG8_WAIT_L(0); PG8_BAR; PG8_MMA(0, 0, At, B0); PG8_MMA(0, 1, At, B1); PG8_BAR; PG8_SCHED;
;             PG8_LDA(At, 1, 1); PG8_STAGE(PG8_SB(1, 0), b3, voffB); PG8_STAGE(PG8_SB(1, 1), b3 + hstepB, voffB); PG8_STAGE(PG8_SA(1, 0), a3, voffA);
;             PG8_WAIT_V(8); PG8_WAIT_L(0); PG8_BAR; PG8_MMA(1, 0, At, B0); PG8_MMA(1, 1, At, B1); PG8_BAR; PG8_SCHED;
;         }
	s_add_i32 s16, s52, s20
	v_lshl_add_u64 v[164:165], v[164:165], 0, s[36:37]
	s_mov_b32 m0, s16
	ds_read_b128 v[202:205], v196 offset:49152
	ds_read_b128 v[206:209], v196 offset:50176
	ds_read_b128 v[210:213], v196 offset:51200
	ds_read_b128 v[214:217], v196 offset:52224
	ds_read_b128 v[226:229], v196 offset:53248
	ds_read_b128 v[230:233], v196 offset:54272
	ds_read_b128 v[234:237], v196 offset:55296
	ds_read_b128 v[238:241], v196 offset:56320
	global_load_lds_dwordx4 v[164:165], off
	s_add_i32 m0, s16, 0x2000
	s_add_u32 s16, s34, 0x40080
	v_lshl_add_u64 v[164:165], v[172:173], 0, s[36:37]
	s_addc_u32 s17, s35, 0
	s_add_i32 s34, s53, s20
	global_load_lds_dwordx4 v[164:165], off
	v_lshl_add_u64 v[164:165], s[16:17], 0, v[176:177]
	s_mov_b32 m0, s34
	s_nop 0
	global_load_lds_dwordx4 v[164:165], off
	v_lshl_add_u64 v[164:165], s[16:17], 0, v[144:145]
	s_add_i32 m0, s34, 0x2000
	s_nop 0
	global_load_lds_dwordx4 v[164:165], off
	v_lshl_add_u64 v[164:165], v[194:195], 0, s[76:77]
	s_mov_b32 m0, s42
	s_nop 0
	global_load_lds_dwordx4 v[164:165], off
	v_lshl_add_u64 v[164:165], v[198:199], 0, s[76:77]
	s_mov_b32 m0, s43
	s_nop 0
	global_load_lds_dwordx4 v[164:165], off
	s_waitcnt vmcnt(8)
	s_waitcnt lgkmcnt(0)
	s_barrier
	s_setprio 1
	v_mfma_f32_16x16x32_bf16 v[60:63], v[128:131], v[202:205], v[60:63]
	v_mfma_f32_16x16x32_bf16 v[56:59], v[136:139], v[202:205], v[56:59]
	v_mfma_f32_16x16x32_bf16 v[52:55], v[128:131], v[210:213], v[52:55]
	v_mfma_f32_16x16x32_bf16 v[44:47], v[136:139], v[210:213], v[44:47]
	v_mfma_f32_16x16x32_bf16 v[36:39], v[128:131], v[226:229], v[36:39]
	v_mfma_f32_16x16x32_bf16 v[28:31], v[136:139], v[226:229], v[28:31]
	v_mfma_f32_16x16x32_bf16 v[20:23], v[128:131], v[234:237], v[20:23]
	v_mfma_f32_16x16x32_bf16 v[12:15], v[136:139], v[234:237], v[12:15]
	v_mfma_f32_16x16x32_bf16 v[60:63], v[132:135], v[206:209], v[60:63]
	v_mfma_f32_16x16x32_bf16 v[56:59], v[140:143], v[206:209], v[56:59]
	v_mfma_f32_16x16x32_bf16 v[52:55], v[132:135], v[214:217], v[52:55]
	v_mfma_f32_16x16x32_bf16 v[44:47], v[140:143], v[214:217], v[44:47]
	v_mfma_f32_16x16x32_bf16 v[36:39], v[132:135], v[230:233], v[36:39]
	v_mfma_f32_16x16x32_bf16 v[28:31], v[140:143], v[230:233], v[28:31]
	v_mfma_f32_16x16x32_bf16 v[20:23], v[132:135], v[238:241], v[20:23]
	v_mfma_f32_16x16x32_bf16 v[12:15], v[140:143], v[238:241], v[12:15]
	s_setprio 0
	s_setprio 1
	v_mfma_f32_16x16x32_bf16 v[48:51], v[156:159], v[202:205], v[48:51]
	v_mfma_f32_16x16x32_bf16 v[40:43], v[168:171], v[202:205], v[40:43]
	v_mfma_f32_16x16x32_bf16 v[32:35], v[156:159], v[210:213], v[32:35]
	v_mfma_f32_16x16x32_bf16 v[24:27], v[168:171], v[210:213], v[24:27]
	v_mfma_f32_16x16x32_bf16 v[16:19], v[156:159], v[226:229], v[16:19]
	v_mfma_f32_16x16x32_bf16 v[8:11], v[168:171], v[226:229], v[8:11]
	v_mfma_f32_16x16x32_bf16 v[4:7], v[156:159], v[234:237], v[4:7]
	v_mfma_f32_16x16x32_bf16 v[0:3], v[168:171], v[234:237], v[0:3]
	v_mfma_f32_16x16x32_bf16 v[48:51], v[160:163], v[206:209], v[48:51]
	v_mfma_f32_16x16x32_bf16 v[40:43], v[178:181], v[206:209], v[40:43]
	v_mfma_f32_16x16x32_bf16 v[32:35], v[160:163], v[214:217], v[32:35]
	v_mfma_f32_16x16x32_bf16 v[24:27], v[178:181], v[214:217], v[24:27]
	v_mfma_f32_16x16x32_bf16 v[16:19], v[160:163], v[230:233], v[16:19]
	v_mfma_f32_16x16x32_bf16 v[8:11], v[178:181], v[230:233], v[8:11]
	v_mfma_f32_16x16x32_bf16 v[4:7], v[160:163], v[238:241], v[4:7]
	v_mfma_f32_16x16x32_bf16 v[0:3], v[178:181], v[238:241], v[0:3]
	s_setprio 0
	s_barrier
	s_add_i32 s51, s51, 2
	s_add_u32 s49, s49, 0x100
	s_addc_u32 s50, s50, 0
	s_cmp_gt_u32 s51, 13
	s_mov_b64 s[16:17], s[28:29]
	s_cbranch_scc0 .LBB0_225
	s_and_b64 vcc, exec, s[6:7]
	s_cbranch_vccz .LBB0_228
	s_barrier

;     __host__ __device__ bool next(int i, Unit& u) const {
;         const long L = (long)i * G + c; if (L >= nwg) return false;
;         int wgid = (int)L; { const int q = nwg / NXCD, r = nwg % NXCD, xcd = wgid % NXCD, off = wgid / NXCD; wgid = (xcd < r ? xcd * (q + 1) : r * (q + 1) + (xcd - r) * q) + off; }
;         const int nig = WGM * nN, gid = wgid / nig, fm = gid * WGM, gsz = (nM - fm) < WGM ? (nM - fm) : WGM;
;         u.pm = fm + ((wgid % nig) % gsz); u.pn = (wgid % nig) / gsz; return true;
;     }
.LBB0_336:
	s_add_i32 s48, s48, 1
	s_mul_i32 s2, s48, s89
	s_mul_hi_u32 s3, s48, s88
	s_add_i32 s3, s3, s2
	s_mul_i32 s2, s48, s88
	s_add_u32 s2, s2, s86
	s_addc_u32 s3, s3, s95
	v_mov_b64_e32 v[0:1], 0xc00
	v_cmp_gt_i64_e32 vcc, s[2:3], v[182:183]
	v_cmp_lt_i64_e64 s[4:5], s[2:3], v[0:1]
	s_cbranch_vccnz .LBB0_338
	s_ashr_i32 s3, s2, 31
	s_lshr_b32 s3, s3, 29
	s_add_i32 s3, s2, s3
	s_ashr_i32 s12, s3, 3
	s_and_b32 s3, s3, -8
	s_sub_i32 s2, s2, s3
	s_cmp_lt_i32 s2, 0
	s_movk_i32 s3, 0x181
	s_cselect_b32 s3, s3, 0x180
	s_mul_i32 s2, s2, s3
	s_add_i32 s2, s2, s12
	s_mul_hi_i32 s3, s2, 0x2aaaaaab
	s_lshr_b32 s12, s3, 31
	s_ashr_i32 s3, s3, 4
	s_add_i32 s3, s3, s12
	s_lshl_b32 s13, s3, 3
	s_sub_i32 s12, 0x100, s13
	s_min_i32 s14, s12, 8
	s_mulk_i32 s3, 0x60
	s_sub_i32 s2, s2, s3
	s_lshr_b32 s12, s2, 3
	s_and_b32 s2, s2, 7
	s_add_i32 s14, s13, s2

; #define PG8_STAGE(bufoff, gbase, voff) do { _Pragma("unroll") for (int _i = 0; _i < 2; ++_i) \
;         __builtin_amdgcn_global_load_lds((const unsigned*)((const char*)(gbase) + (voff)[_i]), (LAS unsigned*)(lds + (bufoff) + ldsw + _i * 8192), 16, 0, 0); } while (0)
; #define PG8_LDA(dst, b, h) do { _Pragma("unroll") for (int m = 0; m < 4; ++m) _Pragma("unroll") for (int k = 0; k < 2; ++k) dst[m][k] = *(const LAS bf16x8*)(lds + PG8_SA(b, h) + aoff + m * 2048 + k * 1024); } while (0)
; #define PG8_LDB(dst, b, h) do { _Pragma("unroll") for (int n = 0; n < 2; ++n) _Pragma("unroll") for (int k = 0; k < 2; ++k) dst[n][k] = *(const LAS bf16x8*)(lds + PG8_SB(b, h) + boff + n * 2048 + k * 1024); } while (0)
; #define PG8_MMA(ai, bj, At, Bt) do { __builtin_amdgcn_s_setprio(1); _Pragma("unroll") for (int m = 0; m < 4; ++m) _Pragma("unroll") for (int n = 0; n < 2; ++n) _Pragma("unroll") for (int k = 0; k < 2; ++k) \
;         acc[ai][bj][m][n] = __builtin_amdgcn_mfma_f32_16x16x32_bf16(Bt[n][k], At[m][k], acc[ai][bj][m][n], 0, 0, 0); __builtin_amdgcn_s_setprio(0); } while (0)
; #define PG8_WAIT_V(n) asm volatile("s_waitcnt vmcnt(" #n ")" ::: "memory")
; template <class Epi>
; __device__ __forceinline__ void gemm_phase(LAS unsigned char* lds, const Gemm g, const StaticOrder& S, const Epi& E, const int tid) {
;     ...
;             PG8_LDB(B0, 0, 0); PG8_LDB(B1, 0, 1); PG8_SCHED; PG8_LDA(At, 0, 0); PG8_STAGE(PG8_SA(1, 1), a1 + hstepA, voffA);
;             PG8_WAIT_V(8); PG8_WAIT_L(0); PG8_BAR; PG8_MMA(0, 0, At, B0); PG8_MMA(0, 1, At, B1); PG8_BAR; PG8_SCHED;
;             PG8_LDA(At, 0, 1); PG8_STAGE(PG8_SB(0, 0), b2, voffB); PG8_STAGE(PG8_SB(0, 1), b2 + hstepB, voffB); PG8_STAGE(PG8_SA(0, 0), a2, voffA);
;             PG8_WAIT_V(8); PG8_WAIT_L(0); PG8_BAR; PG8_MMA(1, 0, At, B0); PG8_MMA(1, 1, At, B1); PG8_BAR; PG8_SCHED;
;             PG8_LDB(B0, 1, 0); PG8_LDB(B1, 1, 1); PG8_SCHED; PG8_LDA(At, 1, 0); PG8_STAGE(PG8_SA(0, 1), a2 + hstepA, voffA);
;             PG8_WAIT_V(8); PG8_WAIT_L(0); PG8_BAR; PG8_MMA(0, 0, At, B0); PG8_MMA(0, 1, At, B1); PG8_BAR; PG8_SCHED;
;             PG8_LDA(At, 1, 1); PG8_STAGE(PG8_SB(1, 0), b3, voffB); PG8_STAGE(PG8_SB(1, 1), b3 + hstepB, voffB); PG8_STAGE(PG8_SA(1, 0), a3, voffA);
;             PG8_WAIT_V(8); PG8_WAIT_L(0); PG8_BAR; PG8_MMA(1, 0, At, B0); PG8_MMA(1, 1, At, B1); PG8_BAR; PG8_SCHED;
;         }
.LBB0_339:
	s_add_u32 s34, s28, 0x1000
	s_addc_u32 s35, s29, 0
	s_add_i32 s56, 0, 0x10000
	s_cmp_eq_u32 s55, 12
	s_cselect_b32 s43, s15, s35
	s_cselect_b32 s42, s51, s34
	v_add_u32_e32 v142, s56, v145
	s_cselect_b32 s41, s13, s54
	s_cselect_b32 s40, s52, s53
	s_add_i32 s57, 0, 0x14000
	ds_read_b128 v[158:161], v142
	ds_read_b128 v[162:165], v142 offset:1024
	ds_read_b128 v[166:169], v142 offset:2048
	ds_read_b128 v[170:173], v142 offset:3072
	v_add_u32_e32 v142, s57, v145
	ds_read_b128 v[194:197], v142
	ds_read_b128 v[202:205], v142 offset:1024
	ds_read_b128 v[206:209], v142 offset:2048
	ds_read_b128 v[210:213], v142 offset:3072
	v_lshl_add_u64 v[146:147], s[28:29], 0, v[138:139]
	s_add_i32 m0, s23, 0xc000
	ds_read_b128 v[214:217], v157
	ds_read_b128 v[226:229], v157 offset:1024
	ds_read_b128 v[230:233], v157 offset:2048
	ds_read_b128 v[234:237], v157 offset:3072
	ds_read_b128 v[238:241], v157 offset:4096
	ds_read_b128 v[242:245], v157 offset:5120
	ds_read_b128 v[246:249], v157 offset:6144
	ds_read_b128 v[178:181], v157 offset:7168
	global_load_lds_dwordx4 v[146:147], off
	v_lshl_add_u64 v[146:147], s[28:29], 0, v[140:141]
	s_add_i32 m0, s23, 0xe000
	s_nop 0
	global_load_lds_dwordx4 v[146:147], off
	s_waitcnt vmcnt(8)
	s_waitcnt lgkmcnt(0)
	s_barrier
	s_setprio 1
	v_mfma_f32_16x16x32_bf16 v[124:127], v[158:161], v[214:217], v[124:127]
	v_mfma_f32_16x16x32_bf16 v[120:123], v[166:169], v[214:217], v[120:123]
	v_mfma_f32_16x16x32_bf16 v[116:119], v[158:161], v[230:233], v[116:119]
	v_mfma_f32_16x16x32_bf16 v[108:111], v[166:169], v[230:233], v[108:111]
	v_mfma_f32_16x16x32_bf16 v[100:103], v[158:161], v[238:241], v[100:103]
	v_mfma_f32_16x16x32_bf16 v[92:95], v[166:169], v[238:241], v[92:95]
	v_mfma_f32_16x16x32_bf16 v[84:87], v[158:161], v[246:249], v[84:87]
	v_mfma_f32_16x16x32_bf16 v[76:79], v[166:169], v[246:249], v[76:79]
	v_mfma_f32_16x16x32_bf16 v[124:127], v[162:165], v[226:229], v[124:127]
	v_mfma_f32_16x16x32_bf16 v[120:123], v[170:173], v[226:229], v[120:123]
	v_mfma_f32_16x16x32_bf16 v[116:119], v[162:165], v[234:237], v[116:119]
	v_mfma_f32_16x16x32_bf16 v[108:111], v[170:173], v[234:237], v[108:111]
	v_mfma_f32_16x16x32_bf16 v[100:103], v[162:165], v[242:245], v[100:103]
	v_mfma_f32_16x16x32_bf16 v[92:95], v[170:173], v[242:245], v[92:95]
	v_mfma_f32_16x16x32_bf16 v[84:87], v[162:165], v[178:181], v[84:87]
	v_mfma_f32_16x16x32_bf16 v[76:79], v[170:173], v[178:181], v[76:79]
	s_setprio 0
	s_setprio 1
	v_mfma_f32_16x16x32_bf16 v[112:115], v[194:197], v[214:217], v[112:115]
	v_mfma_f32_16x16x32_bf16 v[104:107], v[206:209], v[214:217], v[104:107]
	v_mfma_f32_16x16x32_bf16 v[96:99], v[194:197], v[230:233], v[96:99]
	v_mfma_f32_16x16x32_bf16 v[88:91], v[206:209], v[230:233], v[88:91]
	v_mfma_f32_16x16x32_bf16 v[80:83], v[194:197], v[238:241], v[80:83]
	v_mfma_f32_16x16x32_bf16 v[72:75], v[206:209], v[238:241], v[72:75]
	v_mfma_f32_16x16x32_bf16 v[68:71], v[194:197], v[246:249], v[68:71]
	v_mfma_f32_16x16x32_bf16 v[64:67], v[206:209], v[246:249], v[64:67]
	v_mfma_f32_16x16x32_bf16 v[112:115], v[202:205], v[226:229], v[112:115]
	v_mfma_f32_16x16x32_bf16 v[104:107], v[210:213], v[226:229], v[104:107]
	v_mfma_f32_16x16x32_bf16 v[96:99], v[202:205], v[234:237], v[96:99]
	v_mfma_f32_16x16x32_bf16 v[88:91], v[210:213], v[234:237], v[88:91]
	v_mfma_f32_16x16x32_bf16 v[80:83], v[202:205], v[242:245], v[80:83]
	v_mfma_f32_16x16x32_bf16 v[72:75], v[210:213], v[242:245], v[72:75]
	v_mfma_f32_16x16x32_bf16 v[68:71], v[202:205], v[178:181], v[68:71]
	v_mfma_f32_16x16x32_bf16 v[64:67], v[210:213], v[178:181], v[64:67]
	s_setprio 0
	s_barrier
	s_add_i32 s28, s56, s22
	v_lshl_add_u64 v[146:147], s[40:41], 0, v[132:133]
	s_mov_b32 m0, s28
	ds_read_b128 v[178:181], v157 offset:16384
	ds_read_b128 v[214:217], v157 offset:17408
	ds_read_b128 v[226:229], v157 offset:18432
	ds_read_b128 v[230:233], v157 offset:19456
	ds_read_b128 v[234:237], v157 offset:20480
	ds_read_b128 v[238:241], v157 offset:21504
	ds_read_b128 v[242:245], v157 offset:22528
	ds_read_b128 v[246:249], v157 offset:23552
	global_load_lds_dwordx4 v[146:147], off
	s_add_i32 m0, s28, 0x2000
	s_add_u32 s28, s40, 0x40000
	v_lshl_add_u64 v[150:151], s[40:41], 0, v[128:129]
	s_addc_u32 s29, s41, 0
	s_add_i32 s56, s57, s22
	global_load_lds_dwordx4 v[150:151], off
	v_lshl_add_u64 v[154:155], s[28:29], 0, v[132:133]
	s_mov_b32 m0, s56
	v_lshl_add_u64 v[174:175], s[42:43], 0, v[130:131]
	global_load_lds_dwordx4 v[154:155], off
	v_lshl_add_u64 v[154:155], s[28:29], 0, v[128:129]
	s_add_i32 m0, s56, 0x2000
	s_nop 0
	global_load_lds_dwordx4 v[154:155], off
	v_lshl_add_u64 v[154:155], s[42:43], 0, v[134:135]
	s_mov_b32 m0, s23
	s_nop 0
	global_load_lds_dwordx4 v[154:155], off
	s_mov_b32 m0, s30
	s_nop 0
	global_load_lds_dwordx4 v[174:175], off
	s_waitcnt vmcnt(8)
	s_waitcnt lgkmcnt(0)
	s_barrier
; #define PG8_STAGE(bufoff, gbase, voff) do { _Pragma("unroll") for (int _i = 0; _i < 2; ++_i) \
;         __builtin_amdgcn_global_load_lds((const unsigned*)((const char*)(gbase) + (voff)[_i]), (LAS unsigned*)(lds + (bufoff) + ldsw + _i * 8192), 16, 0, 0); } while (0)
; #define PG8_LDA(dst, b, h) do { _Pragma("unroll") for (int m = 0; m < 4; ++m) _Pragma("unroll") for (int k = 0; k < 2; ++k) dst[m][k] = *(const LAS bf16x8*)(lds + PG8_SA(b, h) + aoff + m * 2048 + k * 1024); } while (0)
; #define PG8_LDB(dst, b, h) do { _Pragma("unroll") for (int n = 0; n < 2; ++n) _Pragma("unroll") for (int k = 0; k < 2; ++k) dst[n][k] = *(const LAS bf16x8*)(lds + PG8_SB(b, h) + boff + n * 2048 + k * 1024); } while (0)
; #define PG8_MMA(ai, bj, At, Bt) do { __builtin_amdgcn_s_setprio(1); _Pragma("unroll") for (int m = 0; m < 4; ++m) _Pragma("unroll") for (int n = 0; n < 2; ++n) _Pragma("unroll") for (int k = 0; k < 2; ++k) \
;         acc[ai][bj][m][n] = __builtin_amdgcn_mfma_f32_16x16x32_bf16(Bt[n][k], At[m][k], acc[ai][bj][m][n], 0, 0, 0); __builtin_amdgcn_s_setprio(0); } while (0)
; #define PG8_WAIT_V(n) asm volatile("s_waitcnt vmcnt(" #n ")" ::: "memory")
; template <class Epi>
; __device__ __forceinline__ void gemm_phase(LAS unsigned char* lds, const Gemm g, const StaticOrder& S, const Epi& E, const int tid) {
;     ...
;             PG8_LDB(B0, 0, 0); PG8_LDB(B1, 0, 1); PG8_SCHED; PG8_LDA(At, 0, 0); PG8_STAGE(PG8_SA(1, 1), a1 + hstepA, voffA);
;             PG8_WAIT_V(8); PG8_WAIT_L(0); PG8_BAR; PG8_MMA(0, 0, At, B0); PG8_MMA(0, 1, At, B1); PG8_BAR; PG8_SCHED;
;             PG8_LDA(At, 0, 1); PG8_STAGE(PG8_SB(0, 0), b2, voffB); PG8_STAGE(PG8_SB(0, 1), b2 + hstepB, voffB); PG8_STAGE(PG8_SA(0, 0), a2, voffA);
;             PG8_WAIT_V(8); PG8_WAIT_L(0); PG8_BAR; PG8_MMA(1, 0, At, B0); PG8_MMA(1, 1, At, B1); PG8_BAR; PG8_SCHED;
;             PG8_LDB(B0, 1, 0); PG8_LDB(B1, 1, 1); PG8_SCHED; PG8_LDA(At, 1, 0); PG8_STAGE(PG8_SA(0, 1), a2 + hstepA, voffA);
;             PG8_WAIT_V(8); PG8_WAIT_L(0); PG8_BAR; PG8_MMA(0, 0, At, B0); PG8_MMA(0, 1, At, B1); PG8_BAR; PG8_SCHED;
;             PG8_LDA(At, 1, 1); PG8_STAGE(PG8_SB(1, 0), b3, voffB); PG8_STAGE(PG8_SB(1, 1), b3 + hstepB, voffB); PG8_STAGE(PG8_SA(1, 0), a3, voffA);
;             PG8_WAIT_V(8); PG8_WAIT_L(0); PG8_BAR; PG8_MMA(1, 0, At, B0); PG8_MMA(1, 1, At, B1); PG8_BAR; PG8_SCHED;
;         }
	s_setprio 1
	v_mfma_f32_16x16x32_bf16 v[60:63], v[158:161], v[178:181], v[60:63]
	v_mfma_f32_16x16x32_bf16 v[56:59], v[166:169], v[178:181], v[56:59]
	v_mfma_f32_16x16x32_bf16 v[52:55], v[158:161], v[226:229], v[52:55]
	v_mfma_f32_16x16x32_bf16 v[44:47], v[166:169], v[226:229], v[44:47]
	v_mfma_f32_16x16x32_bf16 v[36:39], v[158:161], v[234:237], v[36:39]
	v_mfma_f32_16x16x32_bf16 v[28:31], v[166:169], v[234:237], v[28:31]
	v_mfma_f32_16x16x32_bf16 v[20:23], v[158:161], v[242:245], v[20:23]
	v_mfma_f32_16x16x32_bf16 v[12:15], v[166:169], v[242:245], v[12:15]
	v_mfma_f32_16x16x32_bf16 v[60:63], v[162:165], v[214:217], v[60:63]
	v_mfma_f32_16x16x32_bf16 v[56:59], v[170:173], v[214:217], v[56:59]
	v_mfma_f32_16x16x32_bf16 v[52:55], v[162:165], v[230:233], v[52:55]
	v_mfma_f32_16x16x32_bf16 v[44:47], v[170:173], v[230:233], v[44:47]
	v_mfma_f32_16x16x32_bf16 v[36:39], v[162:165], v[238:241], v[36:39]
	v_mfma_f32_16x16x32_bf16 v[28:31], v[170:173], v[238:241], v[28:31]
	v_mfma_f32_16x16x32_bf16 v[20:23], v[162:165], v[246:249], v[20:23]
	v_mfma_f32_16x16x32_bf16 v[12:15], v[170:173], v[246:249], v[12:15]
	s_setprio 0
	s_setprio 1
	v_mfma_f32_16x16x32_bf16 v[48:51], v[194:197], v[178:181], v[48:51]
	v_mfma_f32_16x16x32_bf16 v[40:43], v[206:209], v[178:181], v[40:43]
	v_mfma_f32_16x16x32_bf16 v[32:35], v[194:197], v[226:229], v[32:35]
	v_mfma_f32_16x16x32_bf16 v[24:27], v[206:209], v[226:229], v[24:27]
	v_mfma_f32_16x16x32_bf16 v[16:19], v[194:197], v[234:237], v[16:19]
	v_mfma_f32_16x16x32_bf16 v[8:11], v[206:209], v[234:237], v[8:11]
	v_mfma_f32_16x16x32_bf16 v[4:7], v[194:197], v[242:245], v[4:7]
	v_mfma_f32_16x16x32_bf16 v[0:3], v[206:209], v[242:245], v[0:3]
	v_mfma_f32_16x16x32_bf16 v[48:51], v[202:205], v[214:217], v[48:51]
	v_mfma_f32_16x16x32_bf16 v[40:43], v[210:213], v[214:217], v[40:43]
	v_mfma_f32_16x16x32_bf16 v[32:35], v[202:205], v[230:233], v[32:35]
	v_mfma_f32_16x16x32_bf16 v[24:27], v[210:213], v[230:233], v[24:27]
	v_mfma_f32_16x16x32_bf16 v[16:19], v[202:205], v[238:241], v[16:19]
	v_mfma_f32_16x16x32_bf16 v[8:11], v[210:213], v[238:241], v[8:11]
	v_mfma_f32_16x16x32_bf16 v[4:7], v[202:205], v[246:249], v[4:7]
	v_mfma_f32_16x16x32_bf16 v[0:3], v[210:213], v[246:249], v[0:3]
	s_setprio 0
	s_barrier
	s_add_i32 s56, 0, 0x18000
	v_add_u32_e32 v142, s56, v145
	s_add_i32 s57, 0, 0x1c000
	ds_read_b128 v[158:161], v142
	ds_read_b128 v[162:165], v142 offset:1024
	ds_read_b128 v[166:169], v142 offset:2048
	ds_read_b128 v[170:173], v142 offset:3072
	v_add_u32_e32 v142, s57, v145
	ds_read_b128 v[178:181], v142
	ds_read_b128 v[194:197], v142 offset:1024
	ds_read_b128 v[202:205], v142 offset:2048
	ds_read_b128 v[206:209], v142 offset:3072
	s_add_u32 s28, s42, 0x40000
	s_addc_u32 s29, s43, 0
	s_mov_b32 m0, s44
	v_lshl_add_u64 v[198:199], s[28:29], 0, v[134:135]
	ds_read_b128 v[210:213], v157 offset:32768
	ds_read_b128 v[214:217], v157 offset:33792
	ds_read_b128 v[226:229], v157 offset:34816
	ds_read_b128 v[230:233], v157 offset:35840
	ds_read_b128 v[234:237], v157 offset:36864
	ds_read_b128 v[238:241], v157 offset:37888
	ds_read_b128 v[242:245], v157 offset:38912
	ds_read_b128 v[246:249], v157 offset:39936
	global_load_lds_dwordx4 v[198:199], off
	v_lshl_add_u64 v[198:199], s[28:29], 0, v[130:131]
	s_mov_b32 m0, s45
	s_nop 0
	global_load_lds_dwordx4 v[198:199], off
	s_waitcnt vmcnt(8)
	s_waitcnt lgkmcnt(0)
	s_barrier
	s_setprio 1
	v_mfma_f32_16x16x32_bf16 v[124:127], v[158:161], v[210:213], v[124:127]
	v_mfma_f32_16x16x32_bf16 v[120:123], v[166:169], v[210:213], v[120:123]
	v_mfma_f32_16x16x32_bf16 v[116:119], v[158:161], v[226:229], v[116:119]
	v_mfma_f32_16x16x32_bf16 v[108:111], v[166:169], v[226:229], v[108:111]
	v_mfma_f32_16x16x32_bf16 v[100:103], v[158:161], v[234:237], v[100:103]
	v_mfma_f32_16x16x32_bf16 v[92:95], v[166:169], v[234:237], v[92:95]
	v_mfma_f32_16x16x32_bf16 v[84:87], v[158:161], v[242:245], v[84:87]
	v_mfma_f32_16x16x32_bf16 v[76:79], v[166:169], v[242:245], v[76:79]
	v_mfma_f32_16x16x32_bf16 v[124:127], v[162:165], v[214:217], v[124:127]
	v_mfma_f32_16x16x32_bf16 v[120:123], v[170:173], v[214:217], v[120:123]
	v_mfma_f32_16x16x32_bf16 v[116:119], v[162:165], v[230:233], v[116:119]
	v_mfma_f32_16x16x32_bf16 v[108:111], v[170:173], v[230:233], v[108:111]
	v_mfma_f32_16x16x32_bf16 v[100:103], v[162:165], v[238:241], v[100:103]
	v_mfma_f32_16x16x32_bf16 v[92:95], v[170:173], v[238:241], v[92:95]
	v_mfma_f32_16x16x32_bf16 v[84:87], v[162:165], v[246:249], v[84:87]
	v_mfma_f32_16x16x32_bf16 v[76:79], v[170:173], v[246:249], v[76:79]
	s_setprio 0
	s_setprio 1
	v_mfma_f32_16x16x32_bf16 v[112:115], v[178:181], v[210:213], v[112:115]
	v_mfma_f32_16x16x32_bf16 v[104:107], v[202:205], v[210:213], v[104:107]
	v_mfma_f32_16x16x32_bf16 v[96:99], v[178:181], v[226:229], v[96:99]
	v_mfma_f32_16x16x32_bf16 v[88:91], v[202:205], v[226:229], v[88:91]
	v_mfma_f32_16x16x32_bf16 v[80:83], v[178:181], v[234:237], v[80:83]
	v_mfma_f32_16x16x32_bf16 v[72:75], v[202:205], v[234:237], v[72:75]
	v_mfma_f32_16x16x32_bf16 v[68:71], v[178:181], v[242:245], v[68:71]
	v_mfma_f32_16x16x32_bf16 v[64:67], v[202:205], v[242:245], v[64:67]
	v_mfma_f32_16x16x32_bf16 v[112:115], v[194:197], v[214:217], v[112:115]
	v_mfma_f32_16x16x32_bf16 v[104:107], v[206:209], v[214:217], v[104:107]
	v_mfma_f32_16x16x32_bf16 v[96:99], v[194:197], v[230:233], v[96:99]
	v_mfma_f32_16x16x32_bf16 v[88:91], v[206:209], v[230:233], v[88:91]
	v_mfma_f32_16x16x32_bf16 v[80:83], v[194:197], v[238:241], v[80:83]
	v_mfma_f32_16x16x32_bf16 v[72:75], v[206:209], v[238:241], v[72:75]
	v_mfma_f32_16x16x32_bf16 v[68:71], v[194:197], v[246:249], v[68:71]
	v_mfma_f32_16x16x32_bf16 v[64:67], v[206:209], v[246:249], v[64:67]
	s_setprio 0
	s_barrier
; #define PG8_STAGE(bufoff, gbase, voff) do { _Pragma("unroll") for (int _i = 0; _i < 2; ++_i) \
;         __builtin_amdgcn_global_load_lds((const unsigned*)((const char*)(gbase) + (voff)[_i]), (LAS unsigned*)(lds + (bufoff) + ldsw + _i * 8192), 16, 0, 0); } while (0)
; #define PG8_LDA(dst, b, h) do { _Pragma("unroll") for (int m = 0; m < 4; ++m) _Pragma("unroll") for (int k = 0; k < 2; ++k) dst[m][k] = *(const LAS bf16x8*)(lds + PG8_SA(b, h) + aoff + m * 2048 + k * 1024); } while (0)
; #define PG8_LDB(dst, b, h) do { _Pragma("unroll") for (int n = 0; n < 2; ++n) _Pragma("unroll") for (int k = 0; k < 2; ++k) dst[n][k] = *(const LAS bf16x8*)(lds + PG8_SB(b, h) + boff + n * 2048 + k * 1024); } while (0)
; #define PG8_MMA(ai, bj, At, Bt) do { __builtin_amdgcn_s_setprio(1); _Pragma("unroll") for (int m = 0; m < 4; ++m) _Pragma("unroll") for (int n = 0; n < 2; ++n) _Pragma("unroll") for (int k = 0; k < 2; ++k) \
;         acc[ai][bj][m][n] = __builtin_amdgcn_mfma_f32_16x16x32_bf16(Bt[n][k], At[m][k], acc[ai][bj][m][n], 0, 0, 0); __builtin_amdgcn_s_setprio(0); } while (0)
; #define PG8_WAIT_V(n) asm volatile("s_waitcnt vmcnt(" #n ")" ::: "memory")
; template <class Epi>
; __device__ __forceinline__ void gemm_phase(LAS unsigned char* lds, const Gemm g, const StaticOrder& S, const Epi& E, const int tid) {
;     ...
;             PG8_LDB(B0, 0, 0); PG8_LDB(B1, 0, 1); PG8_SCHED; PG8_LDA(At, 0, 0); PG8_STAGE(PG8_SA(1, 1), a1 + hstepA, voffA);
;             PG8_WAIT_V(8); PG8_WAIT_L(0); PG8_BAR; PG8_MMA(0, 0, At, B0); PG8_MMA(0, 1, At, B1); PG8_BAR; PG8_SCHED;
;             PG8_LDA(At, 0, 1); PG8_STAGE(PG8_SB(0, 0), b2, voffB); PG8_STAGE(PG8_SB(0, 1), b2 + hstepB, voffB); PG8_STAGE(PG8_SA(0, 0), a2, voffA);
;             PG8_WAIT_V(8); PG8_WAIT_L(0); PG8_BAR; PG8_MMA(1, 0, At, B0); PG8_MMA(1, 1, At, B1); PG8_BAR; PG8_SCHED;
;             PG8_LDB(B0, 1, 0); PG8_LDB(B1, 1, 1); PG8_SCHED; PG8_LDA(At, 1, 0); PG8_STAGE(PG8_SA(0, 1), a2 + hstepA, voffA);
;             PG8_WAIT_V(8); PG8_WAIT_L(0); PG8_BAR; PG8_MMA(0, 0, At, B0); PG8_MMA(0, 1, At, B1); PG8_BAR; PG8_SCHED;
;             PG8_LDA(At, 1, 1); PG8_STAGE(PG8_SB(1, 0), b3, voffB); PG8_STAGE(PG8_SB(1, 1), b3 + hstepB, voffB); PG8_STAGE(PG8_SA(1, 0), a3, voffA);
;             PG8_WAIT_V(8); PG8_WAIT_L(0); PG8_BAR; PG8_MMA(1, 0, At, B0); PG8_MMA(1, 1, At, B1); PG8_BAR; PG8_SCHED;
;         }
	s_add_i32 s28, s56, s22
	v_lshl_add_u64 v[146:147], v[146:147], 0, s[36:37]
	s_mov_b32 m0, s28
	ds_read_b128 v[210:213], v157 offset:49152
	ds_read_b128 v[214:217], v157 offset:50176
	ds_read_b128 v[226:229], v157 offset:51200
	ds_read_b128 v[230:233], v157 offset:52224
	ds_read_b128 v[234:237], v157 offset:53248
	ds_read_b128 v[238:241], v157 offset:54272
	ds_read_b128 v[242:245], v157 offset:55296
	ds_read_b128 v[246:249], v157 offset:56320
	global_load_lds_dwordx4 v[146:147], off
	s_add_i32 m0, s28, 0x2000
	s_add_u32 s28, s40, 0x40080
	v_lshl_add_u64 v[146:147], v[150:151], 0, s[36:37]
	s_addc_u32 s29, s41, 0
	s_add_i32 s40, s57, s22
	global_load_lds_dwordx4 v[146:147], off
	v_lshl_add_u64 v[146:147], s[28:29], 0, v[132:133]
	s_mov_b32 m0, s40
	s_nop 0
	global_load_lds_dwordx4 v[146:147], off
	v_lshl_add_u64 v[146:147], s[28:29], 0, v[128:129]
	s_add_i32 m0, s40, 0x2000
	s_nop 0
	global_load_lds_dwordx4 v[146:147], off
	v_lshl_add_u64 v[146:147], v[154:155], 0, s[76:77]
	s_mov_b32 m0, s46
	s_nop 0
	global_load_lds_dwordx4 v[146:147], off
	v_lshl_add_u64 v[146:147], v[174:175], 0, s[76:77]
	s_mov_b32 m0, s47
	s_nop 0
	global_load_lds_dwordx4 v[146:147], off
	s_waitcnt vmcnt(8)
	s_waitcnt lgkmcnt(0)
	s_barrier
	s_setprio 1
	v_mfma_f32_16x16x32_bf16 v[60:63], v[158:161], v[210:213], v[60:63]
	v_mfma_f32_16x16x32_bf16 v[56:59], v[166:169], v[210:213], v[56:59]
	v_mfma_f32_16x16x32_bf16 v[52:55], v[158:161], v[226:229], v[52:55]
	v_mfma_f32_16x16x32_bf16 v[44:47], v[166:169], v[226:229], v[44:47]
	v_mfma_f32_16x16x32_bf16 v[36:39], v[158:161], v[234:237], v[36:39]
	v_mfma_f32_16x16x32_bf16 v[28:31], v[166:169], v[234:237], v[28:31]
	v_mfma_f32_16x16x32_bf16 v[20:23], v[158:161], v[242:245], v[20:23]
	v_mfma_f32_16x16x32_bf16 v[12:15], v[166:169], v[242:245], v[12:15]
	v_mfma_f32_16x16x32_bf16 v[60:63], v[162:165], v[214:217], v[60:63]
	v_mfma_f32_16x16x32_bf16 v[56:59], v[170:173], v[214:217], v[56:59]
	v_mfma_f32_16x16x32_bf16 v[52:55], v[162:165], v[230:233], v[52:55]
	v_mfma_f32_16x16x32_bf16 v[44:47], v[170:173], v[230:233], v[44:47]
	v_mfma_f32_16x16x32_bf16 v[36:39], v[162:165], v[238:241], v[36:39]
	v_mfma_f32_16x16x32_bf16 v[28:31], v[170:173], v[238:241], v[28:31]
	v_mfma_f32_16x16x32_bf16 v[20:23], v[162:165], v[246:249], v[20:23]
	v_mfma_f32_16x16x32_bf16 v[12:15], v[170:173], v[246:249], v[12:15]
	s_setprio 0
	s_setprio 1
	v_mfma_f32_16x16x32_bf16 v[48:51], v[178:181], v[210:213], v[48:51]
	v_mfma_f32_16x16x32_bf16 v[40:43], v[202:205], v[210:213], v[40:43]
	v_mfma_f32_16x16x32_bf16 v[32:35], v[178:181], v[226:229], v[32:35]
	v_mfma_f32_16x16x32_bf16 v[24:27], v[202:205], v[226:229], v[24:27]
	v_mfma_f32_16x16x32_bf16 v[16:19], v[178:181], v[234:237], v[16:19]
	v_mfma_f32_16x16x32_bf16 v[8:11], v[202:205], v[234:237], v[8:11]
	v_mfma_f32_16x16x32_bf16 v[4:7], v[178:181], v[242:245], v[4:7]
	v_mfma_f32_16x16x32_bf16 v[0:3], v[202:205], v[242:245], v[0:3]
	v_mfma_f32_16x16x32_bf16 v[48:51], v[194:197], v[214:217], v[48:51]
	v_mfma_f32_16x16x32_bf16 v[40:43], v[206:209], v[214:217], v[40:43]
	v_mfma_f32_16x16x32_bf16 v[32:35], v[194:197], v[230:233], v[32:35]
	v_mfma_f32_16x16x32_bf16 v[24:27], v[206:209], v[230:233], v[24:27]
	v_mfma_f32_16x16x32_bf16 v[16:19], v[194:197], v[238:241], v[16:19]
	v_mfma_f32_16x16x32_bf16 v[8:11], v[206:209], v[238:241], v[8:11]
	v_mfma_f32_16x16x32_bf16 v[4:7], v[194:197], v[246:249], v[4:7]
	v_mfma_f32_16x16x32_bf16 v[0:3], v[206:209], v[246:249], v[0:3]
	s_setprio 0
	s_barrier
	s_add_i32 s55, s55, 2
	s_add_u32 s53, s53, 0x100
	s_addc_u32 s54, s54, 0
	s_cmp_gt_u32 s55, 13
	s_mov_b64 s[28:29], s[34:35]
	s_cbranch_scc0 .LBB0_339
	s_and_b64 vcc, exec, s[10:11]
	s_cbranch_vccz .LBB0_342
	s_barrier

;     __host__ __device__ bool next(int i, Unit& u) const {
;         const long L = (long)i * G + c; if (L >= nwg) return false;
;         int wgid = (int)L; { const int q = nwg / NXCD, r = nwg % NXCD, xcd = wgid % NXCD, off = wgid / NXCD; wgid = (xcd < r ? xcd * (q + 1) : r * (q + 1) + (xcd - r) * q) + off; }
;         const int nig = WGM * nN, gid = wgid / nig, fm = gid * WGM, gsz = (nM - fm) < WGM ? (nM - fm) : WGM;
;         u.pm = fm + ((wgid % nig) % gsz); u.pn = (wgid % nig) / gsz; return true;
;     }
.LBB0_387:
	s_ashr_i32 s6, s34, 3
	s_add_i32 s6, s50, s6
	s_ashr_i32 s7, s6, 31
	s_lshr_b32 s7, s7, 27
	s_add_i32 s7, s6, s7
	s_ashr_i32 s34, s7, 5
	s_lshl_b32 s34, s34, 3
	s_sub_i32 s35, 0x100, s34
	s_min_i32 s35, s35, 8
	s_andn2_b32 s7, s7, 31
	s_sub_i32 s6, s6, s7
	s_lshr_b32 s68, s6, 3
	s_and_b32 s6, s6, 7
	s_add_i32 s69, s34, s6

; #define PG8_STAGE(bufoff, gbase, voff) do { _Pragma("unroll") for (int _i = 0; _i < 2; ++_i) \
;         __builtin_amdgcn_global_load_lds((const unsigned*)((const char*)(gbase) + (voff)[_i]), (LAS unsigned*)(lds + (bufoff) + ldsw + _i * 8192), 16, 0, 0); } while (0)
; #define PG8_LDA(dst, b, h) do { _Pragma("unroll") for (int m = 0; m < 4; ++m) _Pragma("unroll") for (int k = 0; k < 2; ++k) dst[m][k] = *(const LAS bf16x8*)(lds + PG8_SA(b, h) + aoff + m * 2048 + k * 1024); } while (0)
; #define PG8_LDB(dst, b, h) do { _Pragma("unroll") for (int n = 0; n < 2; ++n) _Pragma("unroll") for (int k = 0; k < 2; ++k) dst[n][k] = *(const LAS bf16x8*)(lds + PG8_SB(b, h) + boff + n * 2048 + k * 1024); } while (0)
; #define PG8_MMA(ai, bj, At, Bt) do { __builtin_amdgcn_s_setprio(1); _Pragma("unroll") for (int m = 0; m < 4; ++m) _Pragma("unroll") for (int n = 0; n < 2; ++n) _Pragma("unroll") for (int k = 0; k < 2; ++k) \
;         acc[ai][bj][m][n] = __builtin_amdgcn_mfma_f32_16x16x32_bf16(Bt[n][k], At[m][k], acc[ai][bj][m][n], 0, 0, 0); __builtin_amdgcn_s_setprio(0); } while (0)
; #define PG8_WAIT_V(n) asm volatile("s_waitcnt vmcnt(" #n ")" ::: "memory")
; template <class Epi>
; __device__ __forceinline__ void gemm_phase(LAS unsigned char* lds, const Gemm g, const StaticOrder& S, const Epi& E, const int tid) {
;     ...
;             PG8_LDB(B0, 0, 0); PG8_LDB(B1, 0, 1); PG8_SCHED; PG8_LDA(At, 0, 0); PG8_STAGE(PG8_SA(1, 1), a1 + hstepA, voffA);
;             PG8_WAIT_V(8); PG8_WAIT_L(0); PG8_BAR; PG8_MMA(0, 0, At, B0); PG8_MMA(0, 1, At, B1); PG8_BAR; PG8_SCHED;
;             PG8_LDA(At, 0, 1); PG8_STAGE(PG8_SB(0, 0), b2, voffB); PG8_STAGE(PG8_SB(0, 1), b2 + hstepB, voffB); PG8_STAGE(PG8_SA(0, 0), a2, voffA);
;             PG8_WAIT_V(8); PG8_WAIT_L(0); PG8_BAR; PG8_MMA(1, 0, At, B0); PG8_MMA(1, 1, At, B1); PG8_BAR; PG8_SCHED;
;             PG8_LDB(B0, 1, 0); PG8_LDB(B1, 1, 1); PG8_SCHED; PG8_LDA(At, 1, 0); PG8_STAGE(PG8_SA(0, 1), a2 + hstepA, voffA);
;             PG8_WAIT_V(8); PG8_WAIT_L(0); PG8_BAR; PG8_MMA(0, 0, At, B0); PG8_MMA(0, 1, At, B1); PG8_BAR; PG8_SCHED;
;             PG8_LDA(At, 1, 1); PG8_STAGE(PG8_SB(1, 0), b3, voffB); PG8_STAGE(PG8_SB(1, 1), b3 + hstepB, voffB); PG8_STAGE(PG8_SA(1, 0), a3, voffA);
;             PG8_WAIT_V(8); PG8_WAIT_L(0); PG8_BAR; PG8_MMA(1, 0, At, B0); PG8_MMA(1, 1, At, B1); PG8_BAR; PG8_SCHED;
;         }
.LBB0_393:
	s_add_u32 s80, s28, 1
	s_addc_u32 s81, s29, 0
	s_add_u32 s34, s28, 2
	s_addc_u32 s35, s29, 0
	s_lshl_b64 s[52:53], s[34:35], s61
	s_add_u32 s29, s2, s52
	s_addc_u32 s52, s3, s53
	s_cmp_eq_u32 s65, s28
	s_cselect_b32 s53, s9, s52
	s_cselect_b32 s52, s8, s29
	s_cselect_b32 s82, s50, s73
	s_cselect_b32 s83, s51, s75
	s_add_u32 s28, s52, s40
	s_addc_u32 s29, s53, s41
	s_add_i32 s84, 0, 0x10000
	s_add_i32 s85, 0, 0x14000
	v_add_u32_e32 v140, s84, v225
	v_add_u32_e32 v156, s85, v225
	ds_read_b128 v[124:127], v140
	ds_read_b128 v[128:131], v140 offset:1024
	ds_read_b128 v[136:139], v140 offset:2048
	ds_read_b128 v[140:143], v140 offset:3072
	ds_read_b128 v[144:147], v156
	ds_read_b128 v[148:151], v156 offset:1024
	ds_read_b128 v[152:155], v156 offset:2048
	ds_read_b128 v[156:159], v156 offset:3072
	s_lshl_b64 s[80:81], s[80:81], s61
	s_add_u32 s80, s71, s80
	s_addc_u32 s81, s72, s81
	v_lshl_add_u64 v[178:179], s[80:81], 0, v[194:195]
	s_add_i32 m0, s23, 0xc000
	ds_read_b128 v[160:163], v226
	ds_read_b128 v[164:167], v226 offset:1024
	ds_read_b128 v[168:171], v226 offset:2048
	ds_read_b128 v[172:175], v226 offset:3072
	ds_read_b128 v[202:205], v226 offset:4096
	ds_read_b128 v[206:209], v226 offset:5120
	ds_read_b128 v[210:213], v226 offset:6144
	ds_read_b128 v[214:217], v226 offset:7168
	global_load_lds_dwordx4 v[178:179], off
	v_lshl_add_u64 v[178:179], s[80:81], 0, v[198:199]
	s_add_i32 m0, s23, 0xe000
	s_nop 0
	global_load_lds_dwordx4 v[178:179], off
	s_waitcnt vmcnt(8)
	s_waitcnt lgkmcnt(0)
	s_barrier
	s_setprio 1
	v_mfma_f32_16x16x32_bf16 v[132:135], v[124:127], v[160:163], v[132:135]
	v_mfma_f32_16x16x32_bf16 v[120:123], v[136:139], v[160:163], v[120:123]
	v_mfma_f32_16x16x32_bf16 v[108:111], v[124:127], v[168:171], v[108:111]
	v_mfma_f32_16x16x32_bf16 v[104:107], v[136:139], v[168:171], v[104:107]
	v_mfma_f32_16x16x32_bf16 v[92:95], v[124:127], v[202:205], v[92:95]
	v_mfma_f32_16x16x32_bf16 v[88:91], v[136:139], v[202:205], v[88:91]
	v_mfma_f32_16x16x32_bf16 v[76:79], v[124:127], v[210:213], v[76:79]
	v_mfma_f32_16x16x32_bf16 v[72:75], v[136:139], v[210:213], v[72:75]
	v_mfma_f32_16x16x32_bf16 v[132:135], v[128:131], v[164:167], v[132:135]
	v_mfma_f32_16x16x32_bf16 v[120:123], v[140:143], v[164:167], v[120:123]
	v_mfma_f32_16x16x32_bf16 v[108:111], v[128:131], v[172:175], v[108:111]
	v_mfma_f32_16x16x32_bf16 v[104:107], v[140:143], v[172:175], v[104:107]
	v_mfma_f32_16x16x32_bf16 v[92:95], v[128:131], v[206:209], v[92:95]
	v_mfma_f32_16x16x32_bf16 v[88:91], v[140:143], v[206:209], v[88:91]
	v_mfma_f32_16x16x32_bf16 v[76:79], v[128:131], v[214:217], v[76:79]
	v_mfma_f32_16x16x32_bf16 v[72:75], v[140:143], v[214:217], v[72:75]
	s_setprio 0
	s_setprio 1
	v_mfma_f32_16x16x32_bf16 v[116:119], v[144:147], v[160:163], v[116:119]
	v_mfma_f32_16x16x32_bf16 v[112:115], v[152:155], v[160:163], v[112:115]
	v_mfma_f32_16x16x32_bf16 v[100:103], v[144:147], v[168:171], v[100:103]
	v_mfma_f32_16x16x32_bf16 v[96:99], v[152:155], v[168:171], v[96:99]
	v_mfma_f32_16x16x32_bf16 v[84:87], v[144:147], v[202:205], v[84:87]
	v_mfma_f32_16x16x32_bf16 v[80:83], v[152:155], v[202:205], v[80:83]
	v_mfma_f32_16x16x32_bf16 v[68:71], v[144:147], v[210:213], v[68:71]
	v_mfma_f32_16x16x32_bf16 v[64:67], v[152:155], v[210:213], v[64:67]
	v_mfma_f32_16x16x32_bf16 v[116:119], v[148:151], v[164:167], v[116:119]
	v_mfma_f32_16x16x32_bf16 v[112:115], v[156:159], v[164:167], v[112:115]
	v_mfma_f32_16x16x32_bf16 v[100:103], v[148:151], v[172:175], v[100:103]
	v_mfma_f32_16x16x32_bf16 v[96:99], v[156:159], v[172:175], v[96:99]
	v_mfma_f32_16x16x32_bf16 v[84:87], v[148:151], v[206:209], v[84:87]
	v_mfma_f32_16x16x32_bf16 v[80:83], v[156:159], v[206:209], v[80:83]
	v_mfma_f32_16x16x32_bf16 v[68:71], v[148:151], v[214:217], v[68:71]
	v_mfma_f32_16x16x32_bf16 v[64:67], v[156:159], v[214:217], v[64:67]
	s_setprio 0
	s_barrier
	s_add_i32 s80, s84, s17
	v_lshl_add_u64 v[178:179], s[82:83], 0, v[176:177]
	s_mov_b32 m0, s80
	ds_read_b128 v[160:163], v226 offset:16384
	ds_read_b128 v[164:167], v226 offset:17408
	ds_read_b128 v[168:171], v226 offset:18432
	ds_read_b128 v[172:175], v226 offset:19456
	ds_read_b128 v[202:205], v226 offset:20480
	ds_read_b128 v[206:209], v226 offset:21504
	ds_read_b128 v[210:213], v226 offset:22528
	ds_read_b128 v[214:217], v226 offset:23552
	global_load_lds_dwordx4 v[178:179], off
	s_add_i32 m0, s80, 0x2000
	s_add_u32 s80, s82, s42
	v_lshl_add_u64 v[180:181], s[82:83], 0, v[196:197]
	s_addc_u32 s81, s83, s43
	s_add_i32 s82, s85, s17
	global_load_lds_dwordx4 v[180:181], off
	v_lshl_add_u64 v[218:219], s[80:81], 0, v[176:177]
	s_mov_b32 m0, s82
	v_lshl_add_u64 v[228:229], s[80:81], 0, v[196:197]
	global_load_lds_dwordx4 v[218:219], off
	s_add_i32 m0, s82, 0x2000
	v_lshl_add_u64 v[230:231], s[52:53], 0, v[194:195]
	global_load_lds_dwordx4 v[228:229], off
	s_mov_b32 m0, s23
	s_nop 0
	global_load_lds_dwordx4 v[230:231], off
	v_lshl_add_u64 v[230:231], s[52:53], 0, v[198:199]
	s_mov_b32 m0, s54
	s_nop 0
	global_load_lds_dwordx4 v[230:231], off
	s_waitcnt vmcnt(8)
	s_waitcnt lgkmcnt(0)
	s_barrier
; #define PG8_STAGE(bufoff, gbase, voff) do { _Pragma("unroll") for (int _i = 0; _i < 2; ++_i) \
;         __builtin_amdgcn_global_load_lds((const unsigned*)((const char*)(gbase) + (voff)[_i]), (LAS unsigned*)(lds + (bufoff) + ldsw + _i * 8192), 16, 0, 0); } while (0)
; #define PG8_LDA(dst, b, h) do { _Pragma("unroll") for (int m = 0; m < 4; ++m) _Pragma("unroll") for (int k = 0; k < 2; ++k) dst[m][k] = *(const LAS bf16x8*)(lds + PG8_SA(b, h) + aoff + m * 2048 + k * 1024); } while (0)
; #define PG8_LDB(dst, b, h) do { _Pragma("unroll") for (int n = 0; n < 2; ++n) _Pragma("unroll") for (int k = 0; k < 2; ++k) dst[n][k] = *(const LAS bf16x8*)(lds + PG8_SB(b, h) + boff + n * 2048 + k * 1024); } while (0)
; #define PG8_MMA(ai, bj, At, Bt) do { __builtin_amdgcn_s_setprio(1); _Pragma("unroll") for (int m = 0; m < 4; ++m) _Pragma("unroll") for (int n = 0; n < 2; ++n) _Pragma("unroll") for (int k = 0; k < 2; ++k) \
;         acc[ai][bj][m][n] = __builtin_amdgcn_mfma_f32_16x16x32_bf16(Bt[n][k], At[m][k], acc[ai][bj][m][n], 0, 0, 0); __builtin_amdgcn_s_setprio(0); } while (0)
; #define PG8_WAIT_V(n) asm volatile("s_waitcnt vmcnt(" #n ")" ::: "memory")
; template <class Epi>
; __device__ __forceinline__ void gemm_phase(LAS unsigned char* lds, const Gemm g, const StaticOrder& S, const Epi& E, const int tid) {
;     ...
;             PG8_LDB(B0, 0, 0); PG8_LDB(B1, 0, 1); PG8_SCHED; PG8_LDA(At, 0, 0); PG8_STAGE(PG8_SA(1, 1), a1 + hstepA, voffA);
;             PG8_WAIT_V(8); PG8_WAIT_L(0); PG8_BAR; PG8_MMA(0, 0, At, B0); PG8_MMA(0, 1, At, B1); PG8_BAR; PG8_SCHED;
;             PG8_LDA(At, 0, 1); PG8_STAGE(PG8_SB(0, 0), b2, voffB); PG8_STAGE(PG8_SB(0, 1), b2 + hstepB, voffB); PG8_STAGE(PG8_SA(0, 0), a2, voffA);
;             PG8_WAIT_V(8); PG8_WAIT_L(0); PG8_BAR; PG8_MMA(1, 0, At, B0); PG8_MMA(1, 1, At, B1); PG8_BAR; PG8_SCHED;
;             PG8_LDB(B0, 1, 0); PG8_LDB(B1, 1, 1); PG8_SCHED; PG8_LDA(At, 1, 0); PG8_STAGE(PG8_SA(0, 1), a2 + hstepA, voffA);
;             PG8_WAIT_V(8); PG8_WAIT_L(0); PG8_BAR; PG8_MMA(0, 0, At, B0); PG8_MMA(0, 1, At, B1); PG8_BAR; PG8_SCHED;
;             PG8_LDA(At, 1, 1); PG8_STAGE(PG8_SB(1, 0), b3, voffB); PG8_STAGE(PG8_SB(1, 1), b3 + hstepB, voffB); PG8_STAGE(PG8_SA(1, 0), a3, voffA);
;             PG8_WAIT_V(8); PG8_WAIT_L(0); PG8_BAR; PG8_MMA(1, 0, At, B0); PG8_MMA(1, 1, At, B1); PG8_BAR; PG8_SCHED;
;         }
	s_setprio 1
	v_mfma_f32_16x16x32_bf16 v[60:63], v[124:127], v[160:163], v[60:63]
	v_mfma_f32_16x16x32_bf16 v[56:59], v[136:139], v[160:163], v[56:59]
	v_mfma_f32_16x16x32_bf16 v[44:47], v[124:127], v[168:171], v[44:47]
	v_mfma_f32_16x16x32_bf16 v[40:43], v[136:139], v[168:171], v[40:43]
	v_mfma_f32_16x16x32_bf16 v[28:31], v[124:127], v[202:205], v[28:31]
	v_mfma_f32_16x16x32_bf16 v[24:27], v[136:139], v[202:205], v[24:27]
	v_mfma_f32_16x16x32_bf16 v[12:15], v[124:127], v[210:213], v[12:15]
	v_mfma_f32_16x16x32_bf16 v[8:11], v[136:139], v[210:213], v[8:11]
	v_mfma_f32_16x16x32_bf16 v[60:63], v[128:131], v[164:167], v[60:63]
	v_mfma_f32_16x16x32_bf16 v[56:59], v[140:143], v[164:167], v[56:59]
	v_mfma_f32_16x16x32_bf16 v[44:47], v[128:131], v[172:175], v[44:47]
	v_mfma_f32_16x16x32_bf16 v[40:43], v[140:143], v[172:175], v[40:43]
	v_mfma_f32_16x16x32_bf16 v[28:31], v[128:131], v[206:209], v[28:31]
	v_mfma_f32_16x16x32_bf16 v[24:27], v[140:143], v[206:209], v[24:27]
	v_mfma_f32_16x16x32_bf16 v[12:15], v[128:131], v[214:217], v[12:15]
	v_mfma_f32_16x16x32_bf16 v[8:11], v[140:143], v[214:217], v[8:11]
	s_setprio 0
	s_setprio 1
	v_mfma_f32_16x16x32_bf16 v[52:55], v[144:147], v[160:163], v[52:55]
	v_mfma_f32_16x16x32_bf16 v[48:51], v[152:155], v[160:163], v[48:51]
	v_mfma_f32_16x16x32_bf16 v[36:39], v[144:147], v[168:171], v[36:39]
	v_mfma_f32_16x16x32_bf16 v[32:35], v[152:155], v[168:171], v[32:35]
	v_mfma_f32_16x16x32_bf16 v[20:23], v[144:147], v[202:205], v[20:23]
	v_mfma_f32_16x16x32_bf16 v[16:19], v[152:155], v[202:205], v[16:19]
	v_mfma_f32_16x16x32_bf16 v[4:7], v[144:147], v[210:213], v[4:7]
	v_mfma_f32_16x16x32_bf16 v[0:3], v[152:155], v[210:213], v[0:3]
	v_mfma_f32_16x16x32_bf16 v[52:55], v[148:151], v[164:167], v[52:55]
	v_mfma_f32_16x16x32_bf16 v[48:51], v[156:159], v[164:167], v[48:51]
	v_mfma_f32_16x16x32_bf16 v[36:39], v[148:151], v[172:175], v[36:39]
	v_mfma_f32_16x16x32_bf16 v[32:35], v[156:159], v[172:175], v[32:35]
	v_mfma_f32_16x16x32_bf16 v[20:23], v[148:151], v[206:209], v[20:23]
	v_mfma_f32_16x16x32_bf16 v[16:19], v[156:159], v[206:209], v[16:19]
	v_mfma_f32_16x16x32_bf16 v[4:7], v[148:151], v[214:217], v[4:7]
	v_mfma_f32_16x16x32_bf16 v[0:3], v[156:159], v[214:217], v[0:3]
	s_setprio 0
	s_barrier
	s_add_i32 s80, 0, 0x18000
	s_add_i32 s81, 0, 0x1c000
	v_add_u32_e32 v140, s80, v225
	v_add_u32_e32 v156, s81, v225
	ds_read_b128 v[124:127], v140
	ds_read_b128 v[128:131], v140 offset:1024
	ds_read_b128 v[136:139], v140 offset:2048
	ds_read_b128 v[140:143], v140 offset:3072
	ds_read_b128 v[144:147], v156
	ds_read_b128 v[148:151], v156 offset:1024
	ds_read_b128 v[152:155], v156 offset:2048
	ds_read_b128 v[156:159], v156 offset:3072
	s_add_u32 s52, s52, s21
	s_addc_u32 s53, s53, 0
	s_mov_b32 m0, s55
	v_lshl_add_u64 v[230:231], s[52:53], 0, v[194:195]
	ds_read_b128 v[160:163], v226 offset:32768
	ds_read_b128 v[164:167], v226 offset:33792
	ds_read_b128 v[168:171], v226 offset:34816
	ds_read_b128 v[172:175], v226 offset:35840
	ds_read_b128 v[202:205], v226 offset:36864
	ds_read_b128 v[206:209], v226 offset:37888
	ds_read_b128 v[210:213], v226 offset:38912
	ds_read_b128 v[214:217], v226 offset:39936
	global_load_lds_dwordx4 v[230:231], off
	v_lshl_add_u64 v[230:231], s[52:53], 0, v[198:199]
	s_mov_b32 m0, s56
	s_nop 0
	global_load_lds_dwordx4 v[230:231], off
	s_waitcnt vmcnt(8)
	s_waitcnt lgkmcnt(0)
	s_barrier
	s_setprio 1
	v_mfma_f32_16x16x32_bf16 v[132:135], v[124:127], v[160:163], v[132:135]
	v_mfma_f32_16x16x32_bf16 v[120:123], v[136:139], v[160:163], v[120:123]
	v_mfma_f32_16x16x32_bf16 v[108:111], v[124:127], v[168:171], v[108:111]
	v_mfma_f32_16x16x32_bf16 v[104:107], v[136:139], v[168:171], v[104:107]
	v_mfma_f32_16x16x32_bf16 v[92:95], v[124:127], v[202:205], v[92:95]
	v_mfma_f32_16x16x32_bf16 v[88:91], v[136:139], v[202:205], v[88:91]
	v_mfma_f32_16x16x32_bf16 v[76:79], v[124:127], v[210:213], v[76:79]
	v_mfma_f32_16x16x32_bf16 v[72:75], v[136:139], v[210:213], v[72:75]
	v_mfma_f32_16x16x32_bf16 v[132:135], v[128:131], v[164:167], v[132:135]
	v_mfma_f32_16x16x32_bf16 v[120:123], v[140:143], v[164:167], v[120:123]
	v_mfma_f32_16x16x32_bf16 v[108:111], v[128:131], v[172:175], v[108:111]
	v_mfma_f32_16x16x32_bf16 v[104:107], v[140:143], v[172:175], v[104:107]
	v_mfma_f32_16x16x32_bf16 v[92:95], v[128:131], v[206:209], v[92:95]
	v_mfma_f32_16x16x32_bf16 v[88:91], v[140:143], v[206:209], v[88:91]
	v_mfma_f32_16x16x32_bf16 v[76:79], v[128:131], v[214:217], v[76:79]
	v_mfma_f32_16x16x32_bf16 v[72:75], v[140:143], v[214:217], v[72:75]
	s_setprio 0
	s_setprio 1
	v_mfma_f32_16x16x32_bf16 v[116:119], v[144:147], v[160:163], v[116:119]
	v_mfma_f32_16x16x32_bf16 v[112:115], v[152:155], v[160:163], v[112:115]
	v_mfma_f32_16x16x32_bf16 v[100:103], v[144:147], v[168:171], v[100:103]
	v_mfma_f32_16x16x32_bf16 v[96:99], v[152:155], v[168:171], v[96:99]
	v_mfma_f32_16x16x32_bf16 v[84:87], v[144:147], v[202:205], v[84:87]
	v_mfma_f32_16x16x32_bf16 v[80:83], v[152:155], v[202:205], v[80:83]
	v_mfma_f32_16x16x32_bf16 v[68:71], v[144:147], v[210:213], v[68:71]
	v_mfma_f32_16x16x32_bf16 v[64:67], v[152:155], v[210:213], v[64:67]
	v_mfma_f32_16x16x32_bf16 v[116:119], v[148:151], v[164:167], v[116:119]
	v_mfma_f32_16x16x32_bf16 v[112:115], v[156:159], v[164:167], v[112:115]
	v_mfma_f32_16x16x32_bf16 v[100:103], v[148:151], v[172:175], v[100:103]
	v_mfma_f32_16x16x32_bf16 v[96:99], v[156:159], v[172:175], v[96:99]
	v_mfma_f32_16x16x32_bf16 v[84:87], v[148:151], v[206:209], v[84:87]
	v_mfma_f32_16x16x32_bf16 v[80:83], v[156:159], v[206:209], v[80:83]
	v_mfma_f32_16x16x32_bf16 v[68:71], v[148:151], v[214:217], v[68:71]
	v_mfma_f32_16x16x32_bf16 v[64:67], v[156:159], v[214:217], v[64:67]
	s_setprio 0
	s_barrier
; #define PG8_STAGE(bufoff, gbase, voff) do { _Pragma("unroll") for (int _i = 0; _i < 2; ++_i) \
;         __builtin_amdgcn_global_load_lds((const unsigned*)((const char*)(gbase) + (voff)[_i]), (LAS unsigned*)(lds + (bufoff) + ldsw + _i * 8192), 16, 0, 0); } while (0)
; #define PG8_LDA(dst, b, h) do { _Pragma("unroll") for (int m = 0; m < 4; ++m) _Pragma("unroll") for (int k = 0; k < 2; ++k) dst[m][k] = *(const LAS bf16x8*)(lds + PG8_SA(b, h) + aoff + m * 2048 + k * 1024); } while (0)
; #define PG8_LDB(dst, b, h) do { _Pragma("unroll") for (int n = 0; n < 2; ++n) _Pragma("unroll") for (int k = 0; k < 2; ++k) dst[n][k] = *(const LAS bf16x8*)(lds + PG8_SB(b, h) + boff + n * 2048 + k * 1024); } while (0)
; #define PG8_MMA(ai, bj, At, Bt) do { __builtin_amdgcn_s_setprio(1); _Pragma("unroll") for (int m = 0; m < 4; ++m) _Pragma("unroll") for (int n = 0; n < 2; ++n) _Pragma("unroll") for (int k = 0; k < 2; ++k) \
;         acc[ai][bj][m][n] = __builtin_amdgcn_mfma_f32_16x16x32_bf16(Bt[n][k], At[m][k], acc[ai][bj][m][n], 0, 0, 0); __builtin_amdgcn_s_setprio(0); } while (0)
; #define PG8_WAIT_V(n) asm volatile("s_waitcnt vmcnt(" #n ")" ::: "memory")
; template <class Epi>
; __device__ __forceinline__ void gemm_phase(LAS unsigned char* lds, const Gemm g, const StaticOrder& S, const Epi& E, const int tid) {
;     ...
;             PG8_LDB(B0, 0, 0); PG8_LDB(B1, 0, 1); PG8_SCHED; PG8_LDA(At, 0, 0); PG8_STAGE(PG8_SA(1, 1), a1 + hstepA, voffA);
;             PG8_WAIT_V(8); PG8_WAIT_L(0); PG8_BAR; PG8_MMA(0, 0, At, B0); PG8_MMA(0, 1, At, B1); PG8_BAR; PG8_SCHED;
;             PG8_LDA(At, 0, 1); PG8_STAGE(PG8_SB(0, 0), b2, voffB); PG8_STAGE(PG8_SB(0, 1), b2 + hstepB, voffB); PG8_STAGE(PG8_SA(0, 0), a2, voffA);
;             PG8_WAIT_V(8); PG8_WAIT_L(0); PG8_BAR; PG8_MMA(1, 0, At, B0); PG8_MMA(1, 1, At, B1); PG8_BAR; PG8_SCHED;
;             PG8_LDB(B0, 1, 0); PG8_LDB(B1, 1, 1); PG8_SCHED; PG8_LDA(At, 1, 0); PG8_STAGE(PG8_SA(0, 1), a2 + hstepA, voffA);
;             PG8_WAIT_V(8); PG8_WAIT_L(0); PG8_BAR; PG8_MMA(0, 0, At, B0); PG8_MMA(0, 1, At, B1); PG8_BAR; PG8_SCHED;
;             PG8_LDA(At, 1, 1); PG8_STAGE(PG8_SB(1, 0), b3, voffB); PG8_STAGE(PG8_SB(1, 1), b3 + hstepB, voffB); PG8_STAGE(PG8_SA(1, 0), a3, voffA);
;             PG8_WAIT_V(8); PG8_WAIT_L(0); PG8_BAR; PG8_MMA(1, 0, At, B0); PG8_MMA(1, 1, At, B1); PG8_BAR; PG8_SCHED;
;         }
	s_add_i32 s52, s80, s17
	v_lshl_add_u64 v[178:179], v[178:179], 0, s[36:37]
	s_mov_b32 m0, s52
	ds_read_b128 v[160:163], v226 offset:49152
	ds_read_b128 v[164:167], v226 offset:50176
	ds_read_b128 v[168:171], v226 offset:51200
	ds_read_b128 v[172:175], v226 offset:52224
	ds_read_b128 v[202:205], v226 offset:53248
	ds_read_b128 v[206:209], v226 offset:54272
	ds_read_b128 v[210:213], v226 offset:55296
	ds_read_b128 v[214:217], v226 offset:56320
	global_load_lds_dwordx4 v[178:179], off
	v_lshl_add_u64 v[178:179], v[180:181], 0, s[36:37]
	s_add_i32 m0, s52, 0x2000
	s_add_i32 s52, s81, s17
	global_load_lds_dwordx4 v[178:179], off
	v_lshl_add_u64 v[178:179], v[218:219], 0, s[36:37]
	s_mov_b32 m0, s52
	s_nop 0
	global_load_lds_dwordx4 v[178:179], off
	v_lshl_add_u64 v[178:179], v[228:229], 0, s[36:37]
	s_add_i32 m0, s52, 0x2000
	s_nop 0
	global_load_lds_dwordx4 v[178:179], off
	v_lshl_add_u64 v[178:179], s[28:29], 0, v[194:195]
	s_mov_b32 m0, s59
	s_nop 0
	global_load_lds_dwordx4 v[178:179], off
	v_lshl_add_u64 v[178:179], s[28:29], 0, v[198:199]
	s_mov_b32 m0, s60
	s_nop 0
	global_load_lds_dwordx4 v[178:179], off
	s_waitcnt vmcnt(8)
	s_waitcnt lgkmcnt(0)
	s_barrier
	s_setprio 1
	v_mfma_f32_16x16x32_bf16 v[60:63], v[124:127], v[160:163], v[60:63]
	v_mfma_f32_16x16x32_bf16 v[56:59], v[136:139], v[160:163], v[56:59]
	v_mfma_f32_16x16x32_bf16 v[44:47], v[124:127], v[168:171], v[44:47]
	v_mfma_f32_16x16x32_bf16 v[40:43], v[136:139], v[168:171], v[40:43]
	v_mfma_f32_16x16x32_bf16 v[28:31], v[124:127], v[202:205], v[28:31]
	v_mfma_f32_16x16x32_bf16 v[24:27], v[136:139], v[202:205], v[24:27]
	v_mfma_f32_16x16x32_bf16 v[12:15], v[124:127], v[210:213], v[12:15]
	v_mfma_f32_16x16x32_bf16 v[8:11], v[136:139], v[210:213], v[8:11]
	v_mfma_f32_16x16x32_bf16 v[60:63], v[128:131], v[164:167], v[60:63]
	v_mfma_f32_16x16x32_bf16 v[56:59], v[140:143], v[164:167], v[56:59]
	v_mfma_f32_16x16x32_bf16 v[44:47], v[128:131], v[172:175], v[44:47]
	v_mfma_f32_16x16x32_bf16 v[40:43], v[140:143], v[172:175], v[40:43]
	v_mfma_f32_16x16x32_bf16 v[28:31], v[128:131], v[206:209], v[28:31]
	v_mfma_f32_16x16x32_bf16 v[24:27], v[140:143], v[206:209], v[24:27]
	v_mfma_f32_16x16x32_bf16 v[12:15], v[128:131], v[214:217], v[12:15]
	v_mfma_f32_16x16x32_bf16 v[8:11], v[140:143], v[214:217], v[8:11]
	s_setprio 0
	s_setprio 1
	v_mfma_f32_16x16x32_bf16 v[52:55], v[144:147], v[160:163], v[52:55]
	v_mfma_f32_16x16x32_bf16 v[48:51], v[152:155], v[160:163], v[48:51]
	v_mfma_f32_16x16x32_bf16 v[36:39], v[144:147], v[168:171], v[36:39]
	v_mfma_f32_16x16x32_bf16 v[32:35], v[152:155], v[168:171], v[32:35]
	v_mfma_f32_16x16x32_bf16 v[20:23], v[144:147], v[202:205], v[20:23]
	v_mfma_f32_16x16x32_bf16 v[16:19], v[152:155], v[202:205], v[16:19]
	v_mfma_f32_16x16x32_bf16 v[4:7], v[144:147], v[210:213], v[4:7]
	v_mfma_f32_16x16x32_bf16 v[0:3], v[152:155], v[210:213], v[0:3]
	v_mfma_f32_16x16x32_bf16 v[52:55], v[148:151], v[164:167], v[52:55]
	v_mfma_f32_16x16x32_bf16 v[48:51], v[156:159], v[164:167], v[48:51]
	v_mfma_f32_16x16x32_bf16 v[36:39], v[148:151], v[172:175], v[36:39]
	v_mfma_f32_16x16x32_bf16 v[32:35], v[156:159], v[172:175], v[32:35]
	v_mfma_f32_16x16x32_bf16 v[20:23], v[148:151], v[206:209], v[20:23]
	v_mfma_f32_16x16x32_bf16 v[16:19], v[156:159], v[206:209], v[16:19]
	v_mfma_f32_16x16x32_bf16 v[4:7], v[148:151], v[214:217], v[4:7]
	v_mfma_f32_16x16x32_bf16 v[0:3], v[156:159], v[214:217], v[0:3]
	s_setprio 0
	s_barrier
	s_add_u32 s73, s73, 0x100
	s_addc_u32 s75, s75, 0
	s_cmp_ge_u32 s34, s58
	s_mov_b64 s[28:29], s[34:35]
	s_cbranch_scc0 .LBB0_393
	s_and_b64 vcc, exec, s[48:49]
	s_cbranch_vccz .LBB0_396
	s_barrier

;     __host__ __device__ bool next(int i, Unit& u) const {
;         const long L = (long)i * G + c; if (L >= nwg) return false;
;         int wgid = (int)L; { const int q = nwg / NXCD, r = nwg % NXCD, xcd = wgid % NXCD, off = wgid / NXCD; wgid = (xcd < r ? xcd * (q + 1) : r * (q + 1) + (xcd - r) * q) + off; }
;         const int nig = WGM * nN, gid = wgid / nig, fm = gid * WGM, gsz = (nM - fm) < WGM ? (nM - fm) : WGM;
;         u.pm = fm + ((wgid % nig) % gsz); u.pn = (wgid % nig) / gsz; return true;
;     }
.LBB0_429:
	s_ashr_i32 s4, s42, 3
	s_add_i32 s4, s55, s4
	s_ashr_i32 s5, s4, 31
	s_lshr_b32 s5, s5, 27
	s_add_i32 s5, s4, s5
	s_ashr_i32 s42, s5, 5
	s_lshl_b32 s42, s42, 3
	s_sub_i32 s43, 0x100, s42
	s_min_i32 s43, s43, 8
	s_andn2_b32 s5, s5, 31
	s_sub_i32 s4, s4, s5
	s_lshr_b32 s55, s4, 3
	s_and_b32 s4, s4, 7
	s_add_i32 s56, s42, s4

; #define PG8_STAGE(bufoff, gbase, voff) do { _Pragma("unroll") for (int _i = 0; _i < 2; ++_i) \
;         __builtin_amdgcn_global_load_lds((const unsigned*)((const char*)(gbase) + (voff)[_i]), (LAS unsigned*)(lds + (bufoff) + ldsw + _i * 8192), 16, 0, 0); } while (0)
; #define PG8_LDA(dst, b, h) do { _Pragma("unroll") for (int m = 0; m < 4; ++m) _Pragma("unroll") for (int k = 0; k < 2; ++k) dst[m][k] = *(const LAS bf16x8*)(lds + PG8_SA(b, h) + aoff + m * 2048 + k * 1024); } while (0)
; #define PG8_LDB(dst, b, h) do { _Pragma("unroll") for (int n = 0; n < 2; ++n) _Pragma("unroll") for (int k = 0; k < 2; ++k) dst[n][k] = *(const LAS bf16x8*)(lds + PG8_SB(b, h) + boff + n * 2048 + k * 1024); } while (0)
; #define PG8_MMA(ai, bj, At, Bt) do { __builtin_amdgcn_s_setprio(1); _Pragma("unroll") for (int m = 0; m < 4; ++m) _Pragma("unroll") for (int n = 0; n < 2; ++n) _Pragma("unroll") for (int k = 0; k < 2; ++k) \
;         acc[ai][bj][m][n] = __builtin_amdgcn_mfma_f32_16x16x32_bf16(Bt[n][k], At[m][k], acc[ai][bj][m][n], 0, 0, 0); __builtin_amdgcn_s_setprio(0); } while (0)
; #define PG8_WAIT_V(n) asm volatile("s_waitcnt vmcnt(" #n ")" ::: "memory")
; #define PG8_WAIT_L(n) asm volatile("s_waitcnt lgkmcnt(" #n ")" ::: "memory")
; #define PG8_BAR __builtin_amdgcn_s_barrier()
; template <class Epi>
; __device__ __forceinline__ void gemm_phase(LAS unsigned char* lds, const Gemm g, const StaticOrder& S, const Epi& E, const int tid) {
;     ...
;             PG8_LDB(B0, 0, 0); PG8_LDB(B1, 0, 1); PG8_SCHED; PG8_LDA(At, 0, 0); PG8_STAGE(PG8_SA(1, 1), a1 + hstepA, voffA);
;             PG8_WAIT_V(8); PG8_WAIT_L(0); PG8_BAR; PG8_MMA(0, 0, At, B0); PG8_MMA(0, 1, At, B1); PG8_BAR; PG8_SCHED;
;             PG8_LDA(At, 0, 1); PG8_STAGE(PG8_SB(0, 0), b2, voffB); PG8_STAGE(PG8_SB(0, 1), b2 + hstepB, voffB); PG8_STAGE(PG8_SA(0, 0), a2, voffA);
;             PG8_WAIT_V(8); PG8_WAIT_L(0); PG8_BAR; PG8_MMA(1, 0, At, B0); PG8_MMA(1, 1, At, B1); PG8_BAR; PG8_SCHED;
;             PG8_LDB(B0, 1, 0); PG8_LDB(B1, 1, 1); PG8_SCHED; PG8_LDA(At, 1, 0); PG8_STAGE(PG8_SA(0, 1), a2 + hstepA, voffA);
;             PG8_WAIT_V(8); PG8_WAIT_L(0); PG8_BAR; PG8_MMA(0, 0, At, B0); PG8_MMA(0, 1, At, B1); PG8_BAR; PG8_SCHED;
;             PG8_LDA(At, 1, 1); PG8_STAGE(PG8_SB(1, 0), b3, voffB); PG8_STAGE(PG8_SB(1, 1), b3 + hstepB, voffB); PG8_STAGE(PG8_SA(1, 0), a3, voffA);
.LBB0_435:
	s_add_i32 s61, s44, 2
	s_add_u32 s62, s2, 0x800
	s_addc_u32 s45, s3, 0
	s_add_i32 s64, 0, 0x10000
	s_cmp_eq_u32 s51, s44
	s_cselect_b32 s45, s7, s45
	s_cselect_b32 s44, s6, s62
	s_cselect_b32 s63, s43, s60
	s_cselect_b32 s62, s42, s59
	s_add_i32 s65, 0, 0x14000
	v_add_u32_e32 v140, s64, v193
	v_add_u32_e32 v156, s65, v193
	ds_read_b128 v[128:131], v140
	ds_read_b128 v[132:135], v140 offset:1024
	ds_read_b128 v[136:139], v140 offset:2048
	ds_read_b128 v[140:143], v140 offset:3072
	ds_read_b128 v[144:147], v156
	ds_read_b128 v[148:151], v156 offset:1024
	ds_read_b128 v[152:155], v156 offset:2048
	ds_read_b128 v[156:159], v156 offset:3072
	v_lshl_add_u64 v[178:179], s[2:3], 0, v[168:169]
	s_add_i32 m0, s22, 0xc000
	ds_read_b128 v[172:175], v195
	ds_read_b128 v[196:199], v195 offset:1024
	ds_read_b128 v[202:205], v195 offset:2048
	ds_read_b128 v[206:209], v195 offset:3072
	ds_read_b128 v[210:213], v195 offset:4096
	ds_read_b128 v[214:217], v195 offset:5120
	ds_read_b128 v[226:229], v195 offset:6144
	ds_read_b128 v[230:233], v195 offset:7168
	global_load_lds_dwordx4 v[178:179], off
	v_lshl_add_u64 v[178:179], s[2:3], 0, v[170:171]
	s_add_i32 m0, s22, 0xe000
	s_nop 0
	global_load_lds_dwordx4 v[178:179], off
	s_waitcnt vmcnt(8)
	s_waitcnt lgkmcnt(0)
	s_barrier
	s_setprio 1
	v_mfma_f32_16x16x32_bf16 v[124:127], v[128:131], v[172:175], v[124:127]
	v_mfma_f32_16x16x32_bf16 v[120:123], v[136:139], v[172:175], v[120:123]
	v_mfma_f32_16x16x32_bf16 v[108:111], v[128:131], v[202:205], v[108:111]
	v_mfma_f32_16x16x32_bf16 v[104:107], v[136:139], v[202:205], v[104:107]
	v_mfma_f32_16x16x32_bf16 v[92:95], v[128:131], v[210:213], v[92:95]
	v_mfma_f32_16x16x32_bf16 v[88:91], v[136:139], v[210:213], v[88:91]
	v_mfma_f32_16x16x32_bf16 v[76:79], v[128:131], v[226:229], v[76:79]
	v_mfma_f32_16x16x32_bf16 v[72:75], v[136:139], v[226:229], v[72:75]
	v_mfma_f32_16x16x32_bf16 v[124:127], v[132:135], v[196:199], v[124:127]
	v_mfma_f32_16x16x32_bf16 v[120:123], v[140:143], v[196:199], v[120:123]
	v_mfma_f32_16x16x32_bf16 v[108:111], v[132:135], v[206:209], v[108:111]
	v_mfma_f32_16x16x32_bf16 v[104:107], v[140:143], v[206:209], v[104:107]
	v_mfma_f32_16x16x32_bf16 v[92:95], v[132:135], v[214:217], v[92:95]
	v_mfma_f32_16x16x32_bf16 v[88:91], v[140:143], v[214:217], v[88:91]
	v_mfma_f32_16x16x32_bf16 v[76:79], v[132:135], v[230:233], v[76:79]
	v_mfma_f32_16x16x32_bf16 v[72:75], v[140:143], v[230:233], v[72:75]
	s_setprio 0
	s_setprio 1
	v_mfma_f32_16x16x32_bf16 v[116:119], v[144:147], v[172:175], v[116:119]
	v_mfma_f32_16x16x32_bf16 v[112:115], v[152:155], v[172:175], v[112:115]
	v_mfma_f32_16x16x32_bf16 v[100:103], v[144:147], v[202:205], v[100:103]
	v_mfma_f32_16x16x32_bf16 v[96:99], v[152:155], v[202:205], v[96:99]
	v_mfma_f32_16x16x32_bf16 v[84:87], v[144:147], v[210:213], v[84:87]
	v_mfma_f32_16x16x32_bf16 v[80:83], v[152:155], v[210:213], v[80:83]
	v_mfma_f32_16x16x32_bf16 v[68:71], v[144:147], v[226:229], v[68:71]
	v_mfma_f32_16x16x32_bf16 v[64:67], v[152:155], v[226:229], v[64:67]
	v_mfma_f32_16x16x32_bf16 v[116:119], v[148:151], v[196:199], v[116:119]
	v_mfma_f32_16x16x32_bf16 v[112:115], v[156:159], v[196:199], v[112:115]
	v_mfma_f32_16x16x32_bf16 v[100:103], v[148:151], v[206:209], v[100:103]
	v_mfma_f32_16x16x32_bf16 v[96:99], v[156:159], v[206:209], v[96:99]
	v_mfma_f32_16x16x32_bf16 v[84:87], v[148:151], v[214:217], v[84:87]
	v_mfma_f32_16x16x32_bf16 v[80:83], v[156:159], v[214:217], v[80:83]
	v_mfma_f32_16x16x32_bf16 v[68:71], v[148:151], v[230:233], v[68:71]
	v_mfma_f32_16x16x32_bf16 v[64:67], v[156:159], v[230:233], v[64:67]
	s_setprio 0
	s_barrier
	s_add_i32 s64, s64, s21
	v_lshl_add_u64 v[178:179], s[62:63], 0, v[164:165]
	s_mov_b32 m0, s64
	ds_read_b128 v[172:175], v195 offset:16384
	ds_read_b128 v[196:199], v195 offset:17408
	ds_read_b128 v[202:205], v195 offset:18432
	ds_read_b128 v[206:209], v195 offset:19456
	ds_read_b128 v[210:213], v195 offset:20480
	ds_read_b128 v[214:217], v195 offset:21504
	ds_read_b128 v[226:229], v195 offset:22528
	ds_read_b128 v[230:233], v195 offset:23552
	global_load_lds_dwordx4 v[178:179], off
	s_add_i32 m0, s64, 0x2000
	v_lshl_add_u64 v[180:181], s[62:63], 0, v[162:163]
	s_add_u32 s62, s62, s8
	s_addc_u32 s63, s63, s9
	s_add_i32 s64, s65, s21
	global_load_lds_dwordx4 v[180:181], off
	v_lshl_add_u64 v[218:219], s[62:63], 0, v[164:165]
	s_mov_b32 m0, s64
	v_lshl_add_u64 v[234:235], s[62:63], 0, v[162:163]
	global_load_lds_dwordx4 v[218:219], off
	s_add_i32 m0, s64, 0x2000
	v_lshl_add_u64 v[236:237], s[44:45], 0, v[176:177]
	global_load_lds_dwordx4 v[234:235], off
	s_mov_b32 m0, s22
	v_lshl_add_u64 v[238:239], s[44:45], 0, v[160:161]
	global_load_lds_dwordx4 v[236:237], off
	s_mov_b32 m0, s23
	s_nop 0
	global_load_lds_dwordx4 v[238:239], off
	s_waitcnt vmcnt(8)
	s_waitcnt lgkmcnt(0)
	s_barrier
; #define PG8_STAGE(bufoff, gbase, voff) do { _Pragma("unroll") for (int _i = 0; _i < 2; ++_i) \
;         __builtin_amdgcn_global_load_lds((const unsigned*)((const char*)(gbase) + (voff)[_i]), (LAS unsigned*)(lds + (bufoff) + ldsw + _i * 8192), 16, 0, 0); } while (0)
; #define PG8_LDA(dst, b, h) do { _Pragma("unroll") for (int m = 0; m < 4; ++m) _Pragma("unroll") for (int k = 0; k < 2; ++k) dst[m][k] = *(const LAS bf16x8*)(lds + PG8_SA(b, h) + aoff + m * 2048 + k * 1024); } while (0)
; #define PG8_LDB(dst, b, h) do { _Pragma("unroll") for (int n = 0; n < 2; ++n) _Pragma("unroll") for (int k = 0; k < 2; ++k) dst[n][k] = *(const LAS bf16x8*)(lds + PG8_SB(b, h) + boff + n * 2048 + k * 1024); } while (0)
; #define PG8_MMA(ai, bj, At, Bt) do { __builtin_amdgcn_s_setprio(1); _Pragma("unroll") for (int m = 0; m < 4; ++m) _Pragma("unroll") for (int n = 0; n < 2; ++n) _Pragma("unroll") for (int k = 0; k < 2; ++k) \
;         acc[ai][bj][m][n] = __builtin_amdgcn_mfma_f32_16x16x32_bf16(Bt[n][k], At[m][k], acc[ai][bj][m][n], 0, 0, 0); __builtin_amdgcn_s_setprio(0); } while (0)
; #define PG8_WAIT_V(n) asm volatile("s_waitcnt vmcnt(" #n ")" ::: "memory")
; #define PG8_WAIT_L(n) asm volatile("s_waitcnt lgkmcnt(" #n ")" ::: "memory")
; #define PG8_BAR __builtin_amdgcn_s_barrier()
; #define PG8_SCHED __builtin_amdgcn_sched_barrier(0)
; template <class Epi>
; __device__ __forceinline__ void gemm_phase(LAS unsigned char* lds, const Gemm g, const StaticOrder& S, const Epi& E, const int tid) {
;     ...
;             PG8_WAIT_V(8); PG8_WAIT_L(0); PG8_BAR; PG8_MMA(1, 0, At, B0); PG8_MMA(1, 1, At, B1); PG8_BAR; PG8_SCHED;
;             PG8_LDB(B0, 1, 0); PG8_LDB(B1, 1, 1); PG8_SCHED; PG8_LDA(At, 1, 0); PG8_STAGE(PG8_SA(0, 1), a2 + hstepA, voffA);
;             PG8_WAIT_V(8); PG8_WAIT_L(0); PG8_BAR; PG8_MMA(0, 0, At, B0); PG8_MMA(0, 1, At, B1); PG8_BAR; PG8_SCHED;
	s_setprio 1
	v_mfma_f32_16x16x32_bf16 v[60:63], v[128:131], v[172:175], v[60:63]
	v_mfma_f32_16x16x32_bf16 v[56:59], v[136:139], v[172:175], v[56:59]
	v_mfma_f32_16x16x32_bf16 v[44:47], v[128:131], v[202:205], v[44:47]
	v_mfma_f32_16x16x32_bf16 v[40:43], v[136:139], v[202:205], v[40:43]
	v_mfma_f32_16x16x32_bf16 v[28:31], v[128:131], v[210:213], v[28:31]
	v_mfma_f32_16x16x32_bf16 v[24:27], v[136:139], v[210:213], v[24:27]
	v_mfma_f32_16x16x32_bf16 v[12:15], v[128:131], v[226:229], v[12:15]
	v_mfma_f32_16x16x32_bf16 v[8:11], v[136:139], v[226:229], v[8:11]
	v_mfma_f32_16x16x32_bf16 v[60:63], v[132:135], v[196:199], v[60:63]
	v_mfma_f32_16x16x32_bf16 v[56:59], v[140:143], v[196:199], v[56:59]
	v_mfma_f32_16x16x32_bf16 v[44:47], v[132:135], v[206:209], v[44:47]
	v_mfma_f32_16x16x32_bf16 v[40:43], v[140:143], v[206:209], v[40:43]
	v_mfma_f32_16x16x32_bf16 v[28:31], v[132:135], v[214:217], v[28:31]
	v_mfma_f32_16x16x32_bf16 v[24:27], v[140:143], v[214:217], v[24:27]
	v_mfma_f32_16x16x32_bf16 v[12:15], v[132:135], v[230:233], v[12:15]
	v_mfma_f32_16x16x32_bf16 v[8:11], v[140:143], v[230:233], v[8:11]
	s_setprio 0
	s_setprio 1
	v_mfma_f32_16x16x32_bf16 v[52:55], v[144:147], v[172:175], v[52:55]
	v_mfma_f32_16x16x32_bf16 v[48:51], v[152:155], v[172:175], v[48:51]
	v_mfma_f32_16x16x32_bf16 v[36:39], v[144:147], v[202:205], v[36:39]
	v_mfma_f32_16x16x32_bf16 v[32:35], v[152:155], v[202:205], v[32:35]
	v_mfma_f32_16x16x32_bf16 v[20:23], v[144:147], v[210:213], v[20:23]
	v_mfma_f32_16x16x32_bf16 v[16:19], v[152:155], v[210:213], v[16:19]
	v_mfma_f32_16x16x32_bf16 v[4:7], v[144:147], v[226:229], v[4:7]
	v_mfma_f32_16x16x32_bf16 v[0:3], v[152:155], v[226:229], v[0:3]
	v_mfma_f32_16x16x32_bf16 v[52:55], v[148:151], v[196:199], v[52:55]
	v_mfma_f32_16x16x32_bf16 v[48:51], v[156:159], v[196:199], v[48:51]
	v_mfma_f32_16x16x32_bf16 v[36:39], v[148:151], v[206:209], v[36:39]
	v_mfma_f32_16x16x32_bf16 v[32:35], v[156:159], v[206:209], v[32:35]
	v_mfma_f32_16x16x32_bf16 v[20:23], v[148:151], v[214:217], v[20:23]
	v_mfma_f32_16x16x32_bf16 v[16:19], v[156:159], v[214:217], v[16:19]
	v_mfma_f32_16x16x32_bf16 v[4:7], v[148:151], v[230:233], v[4:7]
	v_mfma_f32_16x16x32_bf16 v[0:3], v[156:159], v[230:233], v[0:3]
	s_setprio 0
	s_barrier
	s_add_i32 s62, 0, 0x18000
	s_add_i32 s63, 0, 0x1c000
	v_add_u32_e32 v140, s62, v193
	v_add_u32_e32 v156, s63, v193
	ds_read_b128 v[128:131], v140
	ds_read_b128 v[132:135], v140 offset:1024
	ds_read_b128 v[136:139], v140 offset:2048
	ds_read_b128 v[140:143], v140 offset:3072
	ds_read_b128 v[144:147], v156
	ds_read_b128 v[148:151], v156 offset:1024
	ds_read_b128 v[152:155], v156 offset:2048
	ds_read_b128 v[156:159], v156 offset:3072
	s_add_u32 s44, s44, s30
	s_addc_u32 s45, s45, 0
	s_mov_b32 m0, s46
	v_lshl_add_u64 v[240:241], s[44:45], 0, v[176:177]
	ds_read_b128 v[172:175], v195 offset:32768
	ds_read_b128 v[196:199], v195 offset:33792
	ds_read_b128 v[202:205], v195 offset:34816
	ds_read_b128 v[206:209], v195 offset:35840
	ds_read_b128 v[210:213], v195 offset:36864
	ds_read_b128 v[214:217], v195 offset:37888
	ds_read_b128 v[226:229], v195 offset:38912
	ds_read_b128 v[230:233], v195 offset:39936
	global_load_lds_dwordx4 v[240:241], off
	v_lshl_add_u64 v[240:241], s[44:45], 0, v[160:161]
	s_mov_b32 m0, s47
	s_nop 0
	global_load_lds_dwordx4 v[240:241], off
	s_waitcnt vmcnt(8)
	s_waitcnt lgkmcnt(0)
	s_barrier
	s_setprio 1
	v_mfma_f32_16x16x32_bf16 v[124:127], v[128:131], v[172:175], v[124:127]
	v_mfma_f32_16x16x32_bf16 v[120:123], v[136:139], v[172:175], v[120:123]
	v_mfma_f32_16x16x32_bf16 v[108:111], v[128:131], v[202:205], v[108:111]
	v_mfma_f32_16x16x32_bf16 v[104:107], v[136:139], v[202:205], v[104:107]
	v_mfma_f32_16x16x32_bf16 v[92:95], v[128:131], v[210:213], v[92:95]
	v_mfma_f32_16x16x32_bf16 v[88:91], v[136:139], v[210:213], v[88:91]
	v_mfma_f32_16x16x32_bf16 v[76:79], v[128:131], v[226:229], v[76:79]
	v_mfma_f32_16x16x32_bf16 v[72:75], v[136:139], v[226:229], v[72:75]
	v_mfma_f32_16x16x32_bf16 v[124:127], v[132:135], v[196:199], v[124:127]
	v_mfma_f32_16x16x32_bf16 v[120:123], v[140:143], v[196:199], v[120:123]
	v_mfma_f32_16x16x32_bf16 v[108:111], v[132:135], v[206:209], v[108:111]
	v_mfma_f32_16x16x32_bf16 v[104:107], v[140:143], v[206:209], v[104:107]
	v_mfma_f32_16x16x32_bf16 v[92:95], v[132:135], v[214:217], v[92:95]
	v_mfma_f32_16x16x32_bf16 v[88:91], v[140:143], v[214:217], v[88:91]
	v_mfma_f32_16x16x32_bf16 v[76:79], v[132:135], v[230:233], v[76:79]
	v_mfma_f32_16x16x32_bf16 v[72:75], v[140:143], v[230:233], v[72:75]
	s_setprio 0
	s_setprio 1
	v_mfma_f32_16x16x32_bf16 v[116:119], v[144:147], v[172:175], v[116:119]
	v_mfma_f32_16x16x32_bf16 v[112:115], v[152:155], v[172:175], v[112:115]
	v_mfma_f32_16x16x32_bf16 v[100:103], v[144:147], v[202:205], v[100:103]
	v_mfma_f32_16x16x32_bf16 v[96:99], v[152:155], v[202:205], v[96:99]
	v_mfma_f32_16x16x32_bf16 v[84:87], v[144:147], v[210:213], v[84:87]
	v_mfma_f32_16x16x32_bf16 v[80:83], v[152:155], v[210:213], v[80:83]
	v_mfma_f32_16x16x32_bf16 v[68:71], v[144:147], v[226:229], v[68:71]
	v_mfma_f32_16x16x32_bf16 v[64:67], v[152:155], v[226:229], v[64:67]
	v_mfma_f32_16x16x32_bf16 v[116:119], v[148:151], v[196:199], v[116:119]
	v_mfma_f32_16x16x32_bf16 v[112:115], v[156:159], v[196:199], v[112:115]
	v_mfma_f32_16x16x32_bf16 v[100:103], v[148:151], v[206:209], v[100:103]
	v_mfma_f32_16x16x32_bf16 v[96:99], v[156:159], v[206:209], v[96:99]
	v_mfma_f32_16x16x32_bf16 v[84:87], v[148:151], v[214:217], v[84:87]
	v_mfma_f32_16x16x32_bf16 v[80:83], v[156:159], v[214:217], v[80:83]
	v_mfma_f32_16x16x32_bf16 v[68:71], v[148:151], v[230:233], v[68:71]
	v_mfma_f32_16x16x32_bf16 v[64:67], v[156:159], v[230:233], v[64:67]
	s_setprio 0
	s_barrier
; #define PG8_STAGE(bufoff, gbase, voff) do { _Pragma("unroll") for (int _i = 0; _i < 2; ++_i) \
;         __builtin_amdgcn_global_load_lds((const unsigned*)((const char*)(gbase) + (voff)[_i]), (LAS unsigned*)(lds + (bufoff) + ldsw + _i * 8192), 16, 0, 0); } while (0)
; #define PG8_LDA(dst, b, h) do { _Pragma("unroll") for (int m = 0; m < 4; ++m) _Pragma("unroll") for (int k = 0; k < 2; ++k) dst[m][k] = *(const LAS bf16x8*)(lds + PG8_SA(b, h) + aoff + m * 2048 + k * 1024); } while (0)
; #define PG8_MMA(ai, bj, At, Bt) do { __builtin_amdgcn_s_setprio(1); _Pragma("unroll") for (int m = 0; m < 4; ++m) _Pragma("unroll") for (int n = 0; n < 2; ++n) _Pragma("unroll") for (int k = 0; k < 2; ++k) \
;         acc[ai][bj][m][n] = __builtin_amdgcn_mfma_f32_16x16x32_bf16(Bt[n][k], At[m][k], acc[ai][bj][m][n], 0, 0, 0); __builtin_amdgcn_s_setprio(0); } while (0)
; #define PG8_WAIT_V(n) asm volatile("s_waitcnt vmcnt(" #n ")" ::: "memory")
; #define PG8_WAIT_L(n) asm volatile("s_waitcnt lgkmcnt(" #n ")" ::: "memory")
; #define PG8_BAR __builtin_amdgcn_s_barrier()
; #define PG8_SCHED __builtin_amdgcn_sched_barrier(0)
; template <class Epi>
; __device__ __forceinline__ void gemm_phase(LAS unsigned char* lds, const Gemm g, const StaticOrder& S, const Epi& E, const int tid) {
;     ...
;             PG8_LDA(At, 1, 1); PG8_STAGE(PG8_SB(1, 0), b3, voffB); PG8_STAGE(PG8_SB(1, 1), b3 + hstepB, voffB); PG8_STAGE(PG8_SA(1, 0), a3, voffA);
;             PG8_WAIT_V(8); PG8_WAIT_L(0); PG8_BAR; PG8_MMA(1, 0, At, B0); PG8_MMA(1, 1, At, B1); PG8_BAR; PG8_SCHED;
;         }
	s_add_i32 s44, s62, s21
	v_lshl_add_u64 v[178:179], v[178:179], 0, s[36:37]
	s_mov_b32 m0, s44
	ds_read_b128 v[172:175], v195 offset:49152
	ds_read_b128 v[196:199], v195 offset:50176
	ds_read_b128 v[202:205], v195 offset:51200
	ds_read_b128 v[206:209], v195 offset:52224
	ds_read_b128 v[210:213], v195 offset:53248
	ds_read_b128 v[214:217], v195 offset:54272
	ds_read_b128 v[226:229], v195 offset:55296
	ds_read_b128 v[230:233], v195 offset:56320
	global_load_lds_dwordx4 v[178:179], off
	v_lshl_add_u64 v[178:179], v[180:181], 0, s[36:37]
	s_add_i32 m0, s44, 0x2000
	s_add_i32 s44, s63, s21
	global_load_lds_dwordx4 v[178:179], off
	v_lshl_add_u64 v[178:179], v[218:219], 0, s[36:37]
	s_mov_b32 m0, s44
	s_nop 0
	global_load_lds_dwordx4 v[178:179], off
	v_lshl_add_u64 v[178:179], v[234:235], 0, s[36:37]
	s_add_i32 m0, s44, 0x2000
	s_nop 0
	global_load_lds_dwordx4 v[178:179], off
	v_lshl_add_u64 v[178:179], v[236:237], 0, s[76:77]
	s_mov_b32 m0, s49
	s_nop 0
	global_load_lds_dwordx4 v[178:179], off
	v_lshl_add_u64 v[178:179], v[238:239], 0, s[76:77]
	s_mov_b32 m0, s50
	s_nop 0
	global_load_lds_dwordx4 v[178:179], off
	s_waitcnt vmcnt(8)
	s_waitcnt lgkmcnt(0)
	s_barrier
	s_setprio 1
	v_mfma_f32_16x16x32_bf16 v[60:63], v[128:131], v[172:175], v[60:63]
	v_mfma_f32_16x16x32_bf16 v[56:59], v[136:139], v[172:175], v[56:59]
	v_mfma_f32_16x16x32_bf16 v[44:47], v[128:131], v[202:205], v[44:47]
	v_mfma_f32_16x16x32_bf16 v[40:43], v[136:139], v[202:205], v[40:43]
	v_mfma_f32_16x16x32_bf16 v[28:31], v[128:131], v[210:213], v[28:31]
	v_mfma_f32_16x16x32_bf16 v[24:27], v[136:139], v[210:213], v[24:27]
	v_mfma_f32_16x16x32_bf16 v[12:15], v[128:131], v[226:229], v[12:15]
	v_mfma_f32_16x16x32_bf16 v[8:11], v[136:139], v[226:229], v[8:11]
	v_mfma_f32_16x16x32_bf16 v[60:63], v[132:135], v[196:199], v[60:63]
	v_mfma_f32_16x16x32_bf16 v[56:59], v[140:143], v[196:199], v[56:59]
	v_mfma_f32_16x16x32_bf16 v[44:47], v[132:135], v[206:209], v[44:47]
	v_mfma_f32_16x16x32_bf16 v[40:43], v[140:143], v[206:209], v[40:43]
	v_mfma_f32_16x16x32_bf16 v[28:31], v[132:135], v[214:217], v[28:31]
	v_mfma_f32_16x16x32_bf16 v[24:27], v[140:143], v[214:217], v[24:27]
	v_mfma_f32_16x16x32_bf16 v[12:15], v[132:135], v[230:233], v[12:15]
	v_mfma_f32_16x16x32_bf16 v[8:11], v[140:143], v[230:233], v[8:11]
	s_setprio 0
	s_setprio 1
	v_mfma_f32_16x16x32_bf16 v[52:55], v[144:147], v[172:175], v[52:55]
	v_mfma_f32_16x16x32_bf16 v[48:51], v[152:155], v[172:175], v[48:51]
	v_mfma_f32_16x16x32_bf16 v[36:39], v[144:147], v[202:205], v[36:39]
	v_mfma_f32_16x16x32_bf16 v[32:35], v[152:155], v[202:205], v[32:35]
	v_mfma_f32_16x16x32_bf16 v[20:23], v[144:147], v[210:213], v[20:23]
	v_mfma_f32_16x16x32_bf16 v[16:19], v[152:155], v[210:213], v[16:19]
	v_mfma_f32_16x16x32_bf16 v[4:7], v[144:147], v[226:229], v[4:7]
	v_mfma_f32_16x16x32_bf16 v[0:3], v[152:155], v[226:229], v[0:3]
	v_mfma_f32_16x16x32_bf16 v[52:55], v[148:151], v[196:199], v[52:55]
	v_mfma_f32_16x16x32_bf16 v[48:51], v[156:159], v[196:199], v[48:51]
	v_mfma_f32_16x16x32_bf16 v[36:39], v[148:151], v[206:209], v[36:39]
	v_mfma_f32_16x16x32_bf16 v[32:35], v[156:159], v[206:209], v[32:35]
	v_mfma_f32_16x16x32_bf16 v[20:23], v[148:151], v[214:217], v[20:23]
	v_mfma_f32_16x16x32_bf16 v[16:19], v[156:159], v[214:217], v[16:19]
	v_mfma_f32_16x16x32_bf16 v[4:7], v[148:151], v[230:233], v[4:7]
	v_mfma_f32_16x16x32_bf16 v[0:3], v[156:159], v[230:233], v[0:3]
	s_setprio 0
	s_barrier
	s_add_u32 s59, s59, 0x100
	s_addc_u32 s60, s60, 0
	s_add_u32 s2, s2, 0x1000
	s_addc_u32 s3, s3, 0
	s_cmp_ge_u32 s61, s48
	s_mov_b32 s44, s61
	s_cbranch_scc0 .LBB0_435
	s_and_b64 vcc, exec, s[40:41]
	s_cbranch_vccz .LBB0_438
	s_barrier

; #define PG8_STAGE(bufoff, gbase, voff) do { _Pragma("unroll") for (int _i = 0; _i < 2; ++_i) \
;         __builtin_amdgcn_global_load_lds((const unsigned*)((const char*)(gbase) + (voff)[_i]), (LAS unsigned*)(lds + (bufoff) + ldsw + _i * 8192), 16, 0, 0); } while (0)
; #define PG8_LDA(dst, b, h) do { _Pragma("unroll") for (int m = 0; m < 4; ++m) _Pragma("unroll") for (int k = 0; k < 2; ++k) dst[m][k] = *(const LAS bf16x8*)(lds + PG8_SA(b, h) + aoff + m * 2048 + k * 1024); } while (0)
; #define PG8_WAIT_V(n) asm volatile("s_waitcnt vmcnt(" #n ")" ::: "memory")
;     __host__ __device__ bool next(int i, Unit& u) const {
;         const long L = (long)i * G + c; if (L >= nwg) return false;
;         int wgid = (int)L; { const int q = nwg / NXCD, r = nwg % NXCD, xcd = wgid % NXCD, off = wgid / NXCD; wgid = (xcd < r ? xcd * (q + 1) : r * (q + 1) + (xcd - r) * q) + off; }
;         const int nig = WGM * nN, gid = wgid / nig, fm = gid * WGM, gsz = (nM - fm) < WGM ? (nM - fm) : WGM;
;         u.pm = fm + ((wgid % nig) % gsz); u.pn = (wgid % nig) / gsz; return true;
;     }
; template <class Epi>
; __device__ __forceinline__ void gemm_phase(LAS unsigned char* lds, const Gemm g, const StaticOrder& S, const Epi& E, const int tid) {
;     ...
;         const bool has_next = S.next(ui + 1, nxt);
;         const char* nA = has_next ? (const char*)g.A + (size_t)nxt.pm * tstepA + (size_t)nxt.pn * pnoffA : cA; const char* nB = has_next ? (const char*)g.Bt + (size_t)nxt.pn * tstepB : cB;
;         for (int t = 0; t < nt; t += 2) {
;             const bool last = (t == nt - 2);
;             const char* a1 = cA + (size_t)(t + 1) * kstepA;
;             const char* a2 = last ? nA : cA + (size_t)(t + 2) * kstepA; const char* b2 = last ? nB : cB + (size_t)(t + 2) * kstep;
;             const char* a3 = a2 + kstepA; const char* b3 = b2 + kstep;
;             PG8_LDB(B0, 0, 0); PG8_LDB(B1, 0, 1); PG8_SCHED; PG8_LDA(At, 0, 0); PG8_STAGE(PG8_SA(1, 1), a1 + hstepA, voffA);
;             PG8_WAIT_V(8); PG8_WAIT_L(0); PG8_BAR; PG8_MMA(0, 0, At, B0); PG8_MMA(0, 1, At, B1); PG8_BAR; PG8_SCHED;
;             PG8_LDA(At, 0, 1); PG8_STAGE(PG8_SB(0, 0), b2, voffB); PG8_STAGE(PG8_SB(0, 1), b2 + hstepB, voffB); PG8_STAGE(PG8_SA(0, 0), a2, voffA);
;             PG8_WAIT_V(8); PG8_WAIT_L(0); PG8_BAR; PG8_MMA(1, 0, At, B0); PG8_MMA(1, 1, At, B1); PG8_BAR; PG8_SCHED;
.LBB0_450:
	s_add_i32 s48, s48, 1
	s_mul_i32 s4, s48, s89
	s_mul_hi_u32 s5, s48, s88
	s_add_i32 s5, s5, s4
	s_mul_i32 s4, s48, s88
	s_add_u32 s14, s4, s86
	s_addc_u32 s15, s5, s95
	v_cmp_gt_i64_e32 vcc, s[14:15], v[190:191]
	v_cmp_lt_i64_e64 s[4:5], s[14:15], v[188:189]
	s_cbranch_vccnz .LBB0_452
	s_ashr_i32 s10, s14, 31
	s_lshr_b32 s10, s10, 29
	s_add_i32 s10, s14, s10
	s_ashr_i32 s11, s10, 3
	s_and_b32 s10, s10, -8
	s_sub_i32 s10, s14, s10
	s_cmp_lt_i32 s10, 0
	s_movk_i32 s12, 0x2c1
	s_cselect_b32 s12, s12, 0x2c0
	s_mul_i32 s10, s10, s12
	s_add_i32 s10, s10, s11
	s_mul_hi_i32 s11, s10, 0x2e8ba2e9
	s_lshr_b32 s12, s11, 31
	s_ashr_i32 s11, s11, 5
	s_add_i32 s11, s11, s12
	s_lshl_b32 s12, s11, 3
	s_sub_i32 s13, 0x100, s12
	s_min_i32 s13, s13, 8
	s_mulk_i32 s11, 0xb0
	s_sub_i32 s11, s10, s11
	s_lshr_b32 s10, s11, 3
	s_and_b32 s11, s11, 7
	s_add_i32 s12, s12, s11
.LBB0_452:
	s_ashr_i32 s13, s12, 31
	s_lshl_b64 s[14:15], s[12:13], 19
	s_add_u32 s14, s24, s14
	s_addc_u32 s15, s25, s15
	s_and_b64 s[16:17], s[4:5], exec
	s_cselect_b32 s13, s15, s3
	s_cselect_b32 s51, s14, s2
	s_ashr_i32 s11, s10, 31
	s_lshl_b64 s[16:17], s[10:11], 19
	s_add_u32 s16, s20, s16
	s_addc_u32 s17, s21, s17
	s_and_b64 s[34:35], s[4:5], exec
	s_cselect_b32 s11, s17, s29
	s_cselect_b32 s52, s16, s28
	s_add_u32 s53, s28, 0x100
	s_addc_u32 s54, s29, 0
	s_mov_b32 s55, -2
	s_add_u32 s28, s2, 0x1000
	s_addc_u32 s29, s3, 0
	s_add_i32 s56, 0, 0x10000
	s_cmp_eq_u32 s55, 12
	s_cselect_b32 s41, s13, s29
	s_cselect_b32 s40, s51, s28
	v_add_u32_e32 v145, s56, v143
	s_cselect_b32 s35, s11, s54
	s_cselect_b32 s34, s52, s53
	s_add_i32 s57, 0, 0x14000
	ds_read_b128 v[146:149], v145
	ds_read_b128 v[150:153], v145 offset:1024
	ds_read_b128 v[154:157], v145 offset:2048
	ds_read_b128 v[158:161], v145 offset:3072
	v_add_u32_e32 v145, s57, v143
	ds_read_b128 v[162:165], v145
	ds_read_b128 v[166:169], v145 offset:1024
	ds_read_b128 v[170:173], v145 offset:2048
	ds_read_b128 v[194:197], v145 offset:3072
	v_lshl_add_u64 v[174:175], s[2:3], 0, v[138:139]
	s_add_i32 m0, s23, 0xc000
	ds_read_b128 v[202:205], v144
	ds_read_b128 v[206:209], v144 offset:1024
	ds_read_b128 v[210:213], v144 offset:2048
	ds_read_b128 v[214:217], v144 offset:3072
	ds_read_b128 v[226:229], v144 offset:4096
	ds_read_b128 v[230:233], v144 offset:5120
	ds_read_b128 v[234:237], v144 offset:6144
	ds_read_b128 v[238:241], v144 offset:7168
	global_load_lds_dwordx4 v[174:175], off
	v_lshl_add_u64 v[174:175], s[2:3], 0, v[140:141]
	s_add_i32 m0, s23, 0xe000
	s_nop 0
	global_load_lds_dwordx4 v[174:175], off
	s_waitcnt vmcnt(8)
	s_waitcnt lgkmcnt(0)
	s_barrier
	s_setprio 1
	v_mfma_f32_16x16x32_bf16 v[124:127], v[146:149], v[202:205], 0
	v_mfma_f32_16x16x32_bf16 v[116:119], v[154:157], v[202:205], 0
	v_mfma_f32_16x16x32_bf16 v[108:111], v[146:149], v[210:213], 0
	v_mfma_f32_16x16x32_bf16 v[100:103], v[154:157], v[210:213], 0
	v_mfma_f32_16x16x32_bf16 v[92:95], v[146:149], v[226:229], 0
	v_mfma_f32_16x16x32_bf16 v[84:87], v[154:157], v[226:229], 0
	v_mfma_f32_16x16x32_bf16 v[76:79], v[146:149], v[234:237], 0
	v_mfma_f32_16x16x32_bf16 v[68:71], v[154:157], v[234:237], 0
	v_mfma_f32_16x16x32_bf16 v[124:127], v[150:153], v[206:209], v[124:127]
	v_mfma_f32_16x16x32_bf16 v[116:119], v[158:161], v[206:209], v[116:119]
	v_mfma_f32_16x16x32_bf16 v[108:111], v[150:153], v[214:217], v[108:111]
	v_mfma_f32_16x16x32_bf16 v[100:103], v[158:161], v[214:217], v[100:103]
	v_mfma_f32_16x16x32_bf16 v[92:95], v[150:153], v[230:233], v[92:95]
	v_mfma_f32_16x16x32_bf16 v[84:87], v[158:161], v[230:233], v[84:87]
	v_mfma_f32_16x16x32_bf16 v[76:79], v[150:153], v[238:241], v[76:79]
	v_mfma_f32_16x16x32_bf16 v[68:71], v[158:161], v[238:241], v[68:71]
	s_setprio 0
	s_setprio 1
	v_mfma_f32_16x16x32_bf16 v[120:123], v[162:165], v[202:205], 0
	v_mfma_f32_16x16x32_bf16 v[112:115], v[170:173], v[202:205], 0
	v_mfma_f32_16x16x32_bf16 v[104:107], v[162:165], v[210:213], 0
	v_mfma_f32_16x16x32_bf16 v[96:99], v[170:173], v[210:213], 0
	v_mfma_f32_16x16x32_bf16 v[88:91], v[162:165], v[226:229], 0
	v_mfma_f32_16x16x32_bf16 v[80:83], v[170:173], v[226:229], 0
	v_mfma_f32_16x16x32_bf16 v[72:75], v[162:165], v[234:237], 0
	v_mfma_f32_16x16x32_bf16 v[64:67], v[170:173], v[234:237], 0
	v_mfma_f32_16x16x32_bf16 v[120:123], v[166:169], v[206:209], v[120:123]
	v_mfma_f32_16x16x32_bf16 v[112:115], v[194:197], v[206:209], v[112:115]
	v_mfma_f32_16x16x32_bf16 v[104:107], v[166:169], v[214:217], v[104:107]
	v_mfma_f32_16x16x32_bf16 v[96:99], v[194:197], v[214:217], v[96:99]
	v_mfma_f32_16x16x32_bf16 v[88:91], v[166:169], v[230:233], v[88:91]
	v_mfma_f32_16x16x32_bf16 v[80:83], v[194:197], v[230:233], v[80:83]
	v_mfma_f32_16x16x32_bf16 v[72:75], v[166:169], v[238:241], v[72:75]
	v_mfma_f32_16x16x32_bf16 v[64:67], v[194:197], v[238:241], v[64:67]
	s_setprio 0
	s_barrier
	s_lshl_b32 s100, s50, 14
	s_add_u32 s100, s82, s100
	s_addc_u32 s101, s83, 0
	s_lshl_b32 m0, s22, 1
	s_add_i32 m0, m0, 0x20800
	s_nop 0
	global_load_lds_dwordx4 v193, s[100:101]
	global_load_lds_dwordx4 v193, s[100:101] offset:1024
	s_add_i32 s2, s56, s22
	v_lshl_add_u64 v[174:175], s[34:35], 0, v[176:177]
	s_mov_b32 m0, s2
	ds_read_b128 v[202:205], v144 offset:16384
	ds_read_b128 v[206:209], v144 offset:17408
	ds_read_b128 v[210:213], v144 offset:18432
	ds_read_b128 v[214:217], v144 offset:19456
	ds_read_b128 v[226:229], v144 offset:20480
	ds_read_b128 v[230:233], v144 offset:21504
	ds_read_b128 v[234:237], v144 offset:22528
	ds_read_b128 v[238:241], v144 offset:23552
	global_load_lds_dwordx4 v[174:175], off
	s_add_i32 m0, s2, 0x2000
	s_add_u32 s2, s34, 0x40000
	v_lshl_add_u64 v[178:179], s[34:35], 0, v[128:129]
	s_addc_u32 s3, s35, 0
	s_add_i32 s56, s57, s22
	global_load_lds_dwordx4 v[178:179], off
	v_lshl_add_u64 v[180:181], s[2:3], 0, v[176:177]
	s_mov_b32 m0, s56
	v_lshl_add_u64 v[198:199], s[40:41], 0, v[130:131]
	global_load_lds_dwordx4 v[180:181], off
	v_lshl_add_u64 v[180:181], s[2:3], 0, v[128:129]
	s_add_i32 m0, s56, 0x2000
	s_nop 0
	global_load_lds_dwordx4 v[180:181], off
	v_lshl_add_u64 v[180:181], s[40:41], 0, v[132:133]
	s_mov_b32 m0, s23
	s_nop 0
	global_load_lds_dwordx4 v[180:181], off
	s_mov_b32 m0, s30
	s_nop 0
	global_load_lds_dwordx4 v[198:199], off
	s_waitcnt vmcnt(8)
	s_waitcnt lgkmcnt(0)
	s_barrier
; #define PG8_STAGE(bufoff, gbase, voff) do { _Pragma("unroll") for (int _i = 0; _i < 2; ++_i) \
;         __builtin_amdgcn_global_load_lds((const unsigned*)((const char*)(gbase) + (voff)[_i]), (LAS unsigned*)(lds + (bufoff) + ldsw + _i * 8192), 16, 0, 0); } while (0)
; #define PG8_LDA(dst, b, h) do { _Pragma("unroll") for (int m = 0; m < 4; ++m) _Pragma("unroll") for (int k = 0; k < 2; ++k) dst[m][k] = *(const LAS bf16x8*)(lds + PG8_SA(b, h) + aoff + m * 2048 + k * 1024); } while (0)
; #define PG8_LDB(dst, b, h) do { _Pragma("unroll") for (int n = 0; n < 2; ++n) _Pragma("unroll") for (int k = 0; k < 2; ++k) dst[n][k] = *(const LAS bf16x8*)(lds + PG8_SB(b, h) + boff + n * 2048 + k * 1024); } while (0)
; #define PG8_MMA(ai, bj, At, Bt) do { __builtin_amdgcn_s_setprio(1); _Pragma("unroll") for (int m = 0; m < 4; ++m) _Pragma("unroll") for (int n = 0; n < 2; ++n) _Pragma("unroll") for (int k = 0; k < 2; ++k) \
;         acc[ai][bj][m][n] = __builtin_amdgcn_mfma_f32_16x16x32_bf16(Bt[n][k], At[m][k], acc[ai][bj][m][n], 0, 0, 0); __builtin_amdgcn_s_setprio(0); } while (0)
; #define PG8_WAIT_V(n) asm volatile("s_waitcnt vmcnt(" #n ")" ::: "memory")
; #define PG8_WAIT_L(n) asm volatile("s_waitcnt lgkmcnt(" #n ")" ::: "memory")
; #define PG8_BAR __builtin_amdgcn_s_barrier()
; #define PG8_SCHED __builtin_amdgcn_sched_barrier(0)
; template <class Epi>
; __device__ __forceinline__ void gemm_phase(LAS unsigned char* lds, const Gemm g, const StaticOrder& S, const Epi& E, const int tid) {
;     ...
;             PG8_WAIT_V(8); PG8_WAIT_L(0); PG8_BAR; PG8_MMA(1, 0, At, B0); PG8_MMA(1, 1, At, B1); PG8_BAR; PG8_SCHED;
;             PG8_LDB(B0, 1, 0); PG8_LDB(B1, 1, 1); PG8_SCHED; PG8_LDA(At, 1, 0); PG8_STAGE(PG8_SA(0, 1), a2 + hstepA, voffA);
;             PG8_WAIT_V(8); PG8_WAIT_L(0); PG8_BAR; PG8_MMA(0, 0, At, B0); PG8_MMA(0, 1, At, B1); PG8_BAR; PG8_SCHED;
	s_setprio 1
	v_mfma_f32_16x16x32_bf16 v[60:63], v[146:149], v[202:205], 0
	v_mfma_f32_16x16x32_bf16 v[52:55], v[154:157], v[202:205], 0
	v_mfma_f32_16x16x32_bf16 v[44:47], v[146:149], v[210:213], 0
	v_mfma_f32_16x16x32_bf16 v[36:39], v[154:157], v[210:213], 0
	v_mfma_f32_16x16x32_bf16 v[28:31], v[146:149], v[226:229], 0
	v_mfma_f32_16x16x32_bf16 v[20:23], v[154:157], v[226:229], 0
	v_mfma_f32_16x16x32_bf16 v[12:15], v[146:149], v[234:237], 0
	v_mfma_f32_16x16x32_bf16 v[4:7], v[154:157], v[234:237], 0
	v_mfma_f32_16x16x32_bf16 v[60:63], v[150:153], v[206:209], v[60:63]
	v_mfma_f32_16x16x32_bf16 v[52:55], v[158:161], v[206:209], v[52:55]
	v_mfma_f32_16x16x32_bf16 v[44:47], v[150:153], v[214:217], v[44:47]
	v_mfma_f32_16x16x32_bf16 v[36:39], v[158:161], v[214:217], v[36:39]
	v_mfma_f32_16x16x32_bf16 v[28:31], v[150:153], v[230:233], v[28:31]
	v_mfma_f32_16x16x32_bf16 v[20:23], v[158:161], v[230:233], v[20:23]
	v_mfma_f32_16x16x32_bf16 v[12:15], v[150:153], v[238:241], v[12:15]
	v_mfma_f32_16x16x32_bf16 v[4:7], v[158:161], v[238:241], v[4:7]
	s_setprio 0
	s_setprio 1
	v_mfma_f32_16x16x32_bf16 v[56:59], v[162:165], v[202:205], 0
	v_mfma_f32_16x16x32_bf16 v[48:51], v[170:173], v[202:205], 0
	v_mfma_f32_16x16x32_bf16 v[40:43], v[162:165], v[210:213], 0
	v_mfma_f32_16x16x32_bf16 v[32:35], v[170:173], v[210:213], 0
	v_mfma_f32_16x16x32_bf16 v[24:27], v[162:165], v[226:229], 0
	v_mfma_f32_16x16x32_bf16 v[16:19], v[170:173], v[226:229], 0
	v_mfma_f32_16x16x32_bf16 v[8:11], v[162:165], v[234:237], 0
	v_mfma_f32_16x16x32_bf16 v[0:3], v[170:173], v[234:237], 0
	v_mfma_f32_16x16x32_bf16 v[56:59], v[166:169], v[206:209], v[56:59]
	v_mfma_f32_16x16x32_bf16 v[48:51], v[194:197], v[206:209], v[48:51]
	v_mfma_f32_16x16x32_bf16 v[40:43], v[166:169], v[214:217], v[40:43]
	v_mfma_f32_16x16x32_bf16 v[32:35], v[194:197], v[214:217], v[32:35]
	v_mfma_f32_16x16x32_bf16 v[24:27], v[166:169], v[230:233], v[24:27]
	v_mfma_f32_16x16x32_bf16 v[16:19], v[194:197], v[230:233], v[16:19]
	v_mfma_f32_16x16x32_bf16 v[8:11], v[166:169], v[238:241], v[8:11]
	v_mfma_f32_16x16x32_bf16 v[0:3], v[194:197], v[238:241], v[0:3]
	s_setprio 0
	s_barrier
	s_add_i32 s56, 0, 0x18000
	v_add_u32_e32 v145, s56, v143
	s_add_i32 s57, 0, 0x1c000
	ds_read_b128 v[146:149], v145
	ds_read_b128 v[150:153], v145 offset:1024
	ds_read_b128 v[154:157], v145 offset:2048
	ds_read_b128 v[158:161], v145 offset:3072
	v_add_u32_e32 v145, s57, v143
	ds_read_b128 v[162:165], v145
	ds_read_b128 v[166:169], v145 offset:1024
	ds_read_b128 v[170:173], v145 offset:2048
	ds_read_b128 v[194:197], v145 offset:3072
	s_add_u32 s2, s40, 0x40000
	s_addc_u32 s3, s41, 0
	s_mov_b32 m0, s42
	v_lshl_add_u64 v[218:219], s[2:3], 0, v[132:133]
	ds_read_b128 v[202:205], v144 offset:32768
	ds_read_b128 v[206:209], v144 offset:33792
	ds_read_b128 v[210:213], v144 offset:34816
	ds_read_b128 v[214:217], v144 offset:35840
	ds_read_b128 v[226:229], v144 offset:36864
	ds_read_b128 v[230:233], v144 offset:37888
	ds_read_b128 v[234:237], v144 offset:38912
	ds_read_b128 v[238:241], v144 offset:39936
	global_load_lds_dwordx4 v[218:219], off
	v_lshl_add_u64 v[218:219], s[2:3], 0, v[130:131]
	s_mov_b32 m0, s43
	s_nop 0
	global_load_lds_dwordx4 v[218:219], off
	s_waitcnt vmcnt(8)
	s_waitcnt lgkmcnt(0)
	s_barrier
	s_setprio 1
	v_mfma_f32_16x16x32_bf16 v[124:127], v[146:149], v[202:205], v[124:127]
	v_mfma_f32_16x16x32_bf16 v[116:119], v[154:157], v[202:205], v[116:119]
	v_mfma_f32_16x16x32_bf16 v[108:111], v[146:149], v[210:213], v[108:111]
	v_mfma_f32_16x16x32_bf16 v[100:103], v[154:157], v[210:213], v[100:103]
	v_mfma_f32_16x16x32_bf16 v[92:95], v[146:149], v[226:229], v[92:95]
	v_mfma_f32_16x16x32_bf16 v[84:87], v[154:157], v[226:229], v[84:87]
	v_mfma_f32_16x16x32_bf16 v[76:79], v[146:149], v[234:237], v[76:79]
	v_mfma_f32_16x16x32_bf16 v[68:71], v[154:157], v[234:237], v[68:71]
	v_mfma_f32_16x16x32_bf16 v[124:127], v[150:153], v[206:209], v[124:127]
	v_mfma_f32_16x16x32_bf16 v[116:119], v[158:161], v[206:209], v[116:119]
	v_mfma_f32_16x16x32_bf16 v[108:111], v[150:153], v[214:217], v[108:111]
	v_mfma_f32_16x16x32_bf16 v[100:103], v[158:161], v[214:217], v[100:103]
	v_mfma_f32_16x16x32_bf16 v[92:95], v[150:153], v[230:233], v[92:95]
	v_mfma_f32_16x16x32_bf16 v[84:87], v[158:161], v[230:233], v[84:87]
	v_mfma_f32_16x16x32_bf16 v[76:79], v[150:153], v[238:241], v[76:79]
	v_mfma_f32_16x16x32_bf16 v[68:71], v[158:161], v[238:241], v[68:71]
	s_setprio 0
	s_setprio 1
	v_mfma_f32_16x16x32_bf16 v[120:123], v[162:165], v[202:205], v[120:123]
	v_mfma_f32_16x16x32_bf16 v[112:115], v[170:173], v[202:205], v[112:115]
	v_mfma_f32_16x16x32_bf16 v[104:107], v[162:165], v[210:213], v[104:107]
	v_mfma_f32_16x16x32_bf16 v[96:99], v[170:173], v[210:213], v[96:99]
	v_mfma_f32_16x16x32_bf16 v[88:91], v[162:165], v[226:229], v[88:91]
	v_mfma_f32_16x16x32_bf16 v[80:83], v[170:173], v[226:229], v[80:83]
	v_mfma_f32_16x16x32_bf16 v[72:75], v[162:165], v[234:237], v[72:75]
	v_mfma_f32_16x16x32_bf16 v[64:67], v[170:173], v[234:237], v[64:67]
	v_mfma_f32_16x16x32_bf16 v[120:123], v[166:169], v[206:209], v[120:123]
	v_mfma_f32_16x16x32_bf16 v[112:115], v[194:197], v[206:209], v[112:115]
	v_mfma_f32_16x16x32_bf16 v[104:107], v[166:169], v[214:217], v[104:107]
	v_mfma_f32_16x16x32_bf16 v[96:99], v[194:197], v[214:217], v[96:99]
	v_mfma_f32_16x16x32_bf16 v[88:91], v[166:169], v[230:233], v[88:91]
	v_mfma_f32_16x16x32_bf16 v[80:83], v[194:197], v[230:233], v[80:83]
	v_mfma_f32_16x16x32_bf16 v[72:75], v[166:169], v[238:241], v[72:75]
	v_mfma_f32_16x16x32_bf16 v[64:67], v[194:197], v[238:241], v[64:67]
	s_setprio 0
	s_barrier
; #define PG8_STAGE(bufoff, gbase, voff) do { _Pragma("unroll") for (int _i = 0; _i < 2; ++_i) \
;         __builtin_amdgcn_global_load_lds((const unsigned*)((const char*)(gbase) + (voff)[_i]), (LAS unsigned*)(lds + (bufoff) + ldsw + _i * 8192), 16, 0, 0); } while (0)
; #define PG8_LDA(dst, b, h) do { _Pragma("unroll") for (int m = 0; m < 4; ++m) _Pragma("unroll") for (int k = 0; k < 2; ++k) dst[m][k] = *(const LAS bf16x8*)(lds + PG8_SA(b, h) + aoff + m * 2048 + k * 1024); } while (0)
; #define PG8_LDB(dst, b, h) do { _Pragma("unroll") for (int n = 0; n < 2; ++n) _Pragma("unroll") for (int k = 0; k < 2; ++k) dst[n][k] = *(const LAS bf16x8*)(lds + PG8_SB(b, h) + boff + n * 2048 + k * 1024); } while (0)
; #define PG8_MMA(ai, bj, At, Bt) do { __builtin_amdgcn_s_setprio(1); _Pragma("unroll") for (int m = 0; m < 4; ++m) _Pragma("unroll") for (int n = 0; n < 2; ++n) _Pragma("unroll") for (int k = 0; k < 2; ++k) \
;         acc[ai][bj][m][n] = __builtin_amdgcn_mfma_f32_16x16x32_bf16(Bt[n][k], At[m][k], acc[ai][bj][m][n], 0, 0, 0); __builtin_amdgcn_s_setprio(0); } while (0)
; #define PG8_WAIT_V(n) asm volatile("s_waitcnt vmcnt(" #n ")" ::: "memory")
; #define PG8_BAR __builtin_amdgcn_s_barrier()
; template <class Epi>
; __device__ __forceinline__ void gemm_phase(LAS unsigned char* lds, const Gemm g, const StaticOrder& S, const Epi& E, const int tid) {
;     ...
;             PG8_LDB(B0, 0, 0); PG8_LDB(B1, 0, 1); PG8_SCHED; PG8_LDA(At, 0, 0); PG8_STAGE(PG8_SA(1, 1), a1 + hstepA, voffA);
;             PG8_WAIT_V(8); PG8_WAIT_L(0); PG8_BAR; PG8_MMA(0, 0, At, B0); PG8_MMA(0, 1, At, B1); PG8_BAR; PG8_SCHED;
;             PG8_LDA(At, 0, 1); PG8_STAGE(PG8_SB(0, 0), b2, voffB); PG8_STAGE(PG8_SB(0, 1), b2 + hstepB, voffB); PG8_STAGE(PG8_SA(0, 0), a2, voffA);
;             PG8_WAIT_V(8); PG8_WAIT_L(0); PG8_BAR; PG8_MMA(1, 0, At, B0); PG8_MMA(1, 1, At, B1); PG8_BAR; PG8_SCHED;
;             PG8_LDB(B0, 1, 0); PG8_LDB(B1, 1, 1); PG8_SCHED; PG8_LDA(At, 1, 0); PG8_STAGE(PG8_SA(0, 1), a2 + hstepA, voffA);
;             PG8_WAIT_V(8); PG8_WAIT_L(0); PG8_BAR; PG8_MMA(0, 0, At, B0); PG8_MMA(0, 1, At, B1); PG8_BAR; PG8_SCHED;
;             PG8_LDA(At, 1, 1); PG8_STAGE(PG8_SB(1, 0), b3, voffB); PG8_STAGE(PG8_SB(1, 1), b3 + hstepB, voffB); PG8_STAGE(PG8_SA(1, 0), a3, voffA);
;             PG8_WAIT_V(8); PG8_WAIT_L(0); PG8_BAR; PG8_MMA(1, 0, At, B0); PG8_MMA(1, 1, At, B1); PG8_BAR; PG8_SCHED;
	s_add_i32 s2, s56, s22
	v_lshl_add_u64 v[174:175], v[174:175], 0, s[36:37]
	s_mov_b32 m0, s2
	ds_read_b128 v[202:205], v144 offset:49152
	ds_read_b128 v[206:209], v144 offset:50176
	ds_read_b128 v[210:213], v144 offset:51200
	ds_read_b128 v[214:217], v144 offset:52224
	ds_read_b128 v[226:229], v144 offset:53248
	ds_read_b128 v[230:233], v144 offset:54272
	ds_read_b128 v[234:237], v144 offset:55296
	ds_read_b128 v[238:241], v144 offset:56320
	global_load_lds_dwordx4 v[174:175], off
	s_add_i32 m0, s2, 0x2000
	s_add_u32 s2, s34, 0x40080
	v_lshl_add_u64 v[174:175], v[178:179], 0, s[36:37]
	s_addc_u32 s3, s35, 0
	s_add_i32 s34, s57, s22
	global_load_lds_dwordx4 v[174:175], off
	v_lshl_add_u64 v[174:175], s[2:3], 0, v[176:177]
	s_mov_b32 m0, s34
	s_nop 0
	global_load_lds_dwordx4 v[174:175], off
	v_lshl_add_u64 v[174:175], s[2:3], 0, v[128:129]
	s_add_i32 m0, s34, 0x2000
	s_nop 0
	global_load_lds_dwordx4 v[174:175], off
	v_lshl_add_u64 v[174:175], v[180:181], 0, s[76:77]
	s_mov_b32 m0, s45
	s_nop 0
	global_load_lds_dwordx4 v[174:175], off
	v_lshl_add_u64 v[174:175], v[198:199], 0, s[76:77]
	s_mov_b32 m0, s46
	s_nop 0
	global_load_lds_dwordx4 v[174:175], off
	s_waitcnt vmcnt(8)
	s_waitcnt lgkmcnt(0)
	s_barrier
	s_setprio 1
	v_mfma_f32_16x16x32_bf16 v[60:63], v[146:149], v[202:205], v[60:63]
	v_mfma_f32_16x16x32_bf16 v[52:55], v[154:157], v[202:205], v[52:55]
	v_mfma_f32_16x16x32_bf16 v[44:47], v[146:149], v[210:213], v[44:47]
	v_mfma_f32_16x16x32_bf16 v[36:39], v[154:157], v[210:213], v[36:39]
	v_mfma_f32_16x16x32_bf16 v[28:31], v[146:149], v[226:229], v[28:31]
	v_mfma_f32_16x16x32_bf16 v[20:23], v[154:157], v[226:229], v[20:23]
	v_mfma_f32_16x16x32_bf16 v[12:15], v[146:149], v[234:237], v[12:15]
	v_mfma_f32_16x16x32_bf16 v[4:7], v[154:157], v[234:237], v[4:7]
	v_mfma_f32_16x16x32_bf16 v[60:63], v[150:153], v[206:209], v[60:63]
	v_mfma_f32_16x16x32_bf16 v[52:55], v[158:161], v[206:209], v[52:55]
	v_mfma_f32_16x16x32_bf16 v[44:47], v[150:153], v[214:217], v[44:47]
	v_mfma_f32_16x16x32_bf16 v[36:39], v[158:161], v[214:217], v[36:39]
	v_mfma_f32_16x16x32_bf16 v[28:31], v[150:153], v[230:233], v[28:31]
	v_mfma_f32_16x16x32_bf16 v[20:23], v[158:161], v[230:233], v[20:23]
	v_mfma_f32_16x16x32_bf16 v[12:15], v[150:153], v[238:241], v[12:15]
	v_mfma_f32_16x16x32_bf16 v[4:7], v[158:161], v[238:241], v[4:7]
	s_setprio 0
	s_setprio 1
	v_mfma_f32_16x16x32_bf16 v[56:59], v[162:165], v[202:205], v[56:59]
	v_mfma_f32_16x16x32_bf16 v[48:51], v[170:173], v[202:205], v[48:51]
	v_mfma_f32_16x16x32_bf16 v[40:43], v[162:165], v[210:213], v[40:43]
	v_mfma_f32_16x16x32_bf16 v[32:35], v[170:173], v[210:213], v[32:35]
	v_mfma_f32_16x16x32_bf16 v[24:27], v[162:165], v[226:229], v[24:27]
	v_mfma_f32_16x16x32_bf16 v[16:19], v[170:173], v[226:229], v[16:19]
	v_mfma_f32_16x16x32_bf16 v[8:11], v[162:165], v[234:237], v[8:11]
	v_mfma_f32_16x16x32_bf16 v[0:3], v[170:173], v[234:237], v[0:3]
	v_mfma_f32_16x16x32_bf16 v[56:59], v[166:169], v[206:209], v[56:59]
	v_mfma_f32_16x16x32_bf16 v[48:51], v[194:197], v[206:209], v[48:51]
	v_mfma_f32_16x16x32_bf16 v[40:43], v[166:169], v[214:217], v[40:43]
	v_mfma_f32_16x16x32_bf16 v[32:35], v[194:197], v[214:217], v[32:35]
	v_mfma_f32_16x16x32_bf16 v[24:27], v[166:169], v[230:233], v[24:27]
	v_mfma_f32_16x16x32_bf16 v[16:19], v[194:197], v[230:233], v[16:19]
	v_mfma_f32_16x16x32_bf16 v[8:11], v[166:169], v[238:241], v[8:11]
	v_mfma_f32_16x16x32_bf16 v[0:3], v[194:197], v[238:241], v[0:3]
	s_setprio 0
	s_barrier
	s_add_i32 s55, s55, 2
	s_add_u32 s53, s53, 0x100
	s_addc_u32 s54, s54, 0
	s_mov_b64 s[2:3], s[28:29]
.LBB0_453:
	s_add_u32 s28, s2, 0x1000
	s_addc_u32 s29, s3, 0
	s_add_i32 s56, 0, 0x10000
	s_cmp_eq_u32 s55, 12
	s_cselect_b32 s41, s13, s29
	s_cselect_b32 s40, s51, s28
	v_add_u32_e32 v145, s56, v143
	s_cselect_b32 s35, s11, s54
	s_cselect_b32 s34, s52, s53
	s_add_i32 s57, 0, 0x14000
	ds_read_b128 v[146:149], v145
	ds_read_b128 v[150:153], v145 offset:1024
	ds_read_b128 v[154:157], v145 offset:2048
	ds_read_b128 v[158:161], v145 offset:3072
	v_add_u32_e32 v145, s57, v143
	ds_read_b128 v[162:165], v145
	ds_read_b128 v[166:169], v145 offset:1024
	ds_read_b128 v[170:173], v145 offset:2048
	ds_read_b128 v[194:197], v145 offset:3072
	v_lshl_add_u64 v[174:175], s[2:3], 0, v[138:139]
	s_add_i32 m0, s23, 0xc000
	ds_read_b128 v[202:205], v144
	ds_read_b128 v[206:209], v144 offset:1024
	ds_read_b128 v[210:213], v144 offset:2048
	ds_read_b128 v[214:217], v144 offset:3072
	ds_read_b128 v[226:229], v144 offset:4096
	ds_read_b128 v[230:233], v144 offset:5120
	ds_read_b128 v[234:237], v144 offset:6144
	ds_read_b128 v[238:241], v144 offset:7168
	global_load_lds_dwordx4 v[174:175], off
	v_lshl_add_u64 v[174:175], s[2:3], 0, v[140:141]
	s_add_i32 m0, s23, 0xe000
	s_nop 0
	global_load_lds_dwordx4 v[174:175], off
	s_waitcnt vmcnt(8)
	s_waitcnt lgkmcnt(0)
	s_barrier
; #define PG8_STAGE(bufoff, gbase, voff) do { _Pragma("unroll") for (int _i = 0; _i < 2; ++_i) \
;         __builtin_amdgcn_global_load_lds((const unsigned*)((const char*)(gbase) + (voff)[_i]), (LAS unsigned*)(lds + (bufoff) + ldsw + _i * 8192), 16, 0, 0); } while (0)
; #define PG8_LDA(dst, b, h) do { _Pragma("unroll") for (int m = 0; m < 4; ++m) _Pragma("unroll") for (int k = 0; k < 2; ++k) dst[m][k] = *(const LAS bf16x8*)(lds + PG8_SA(b, h) + aoff + m * 2048 + k * 1024); } while (0)
; #define PG8_MMA(ai, bj, At, Bt) do { __builtin_amdgcn_s_setprio(1); _Pragma("unroll") for (int m = 0; m < 4; ++m) _Pragma("unroll") for (int n = 0; n < 2; ++n) _Pragma("unroll") for (int k = 0; k < 2; ++k) \
;         acc[ai][bj][m][n] = __builtin_amdgcn_mfma_f32_16x16x32_bf16(Bt[n][k], At[m][k], acc[ai][bj][m][n], 0, 0, 0); __builtin_amdgcn_s_setprio(0); } while (0)
; #define PG8_WAIT_V(n) asm volatile("s_waitcnt vmcnt(" #n ")" ::: "memory")
; #define PG8_WAIT_L(n) asm volatile("s_waitcnt lgkmcnt(" #n ")" ::: "memory")
; #define PG8_BAR __builtin_amdgcn_s_barrier()
; #define PG8_SCHED __builtin_amdgcn_sched_barrier(0)
; template <class Epi>
; __device__ __forceinline__ void gemm_phase(LAS unsigned char* lds, const Gemm g, const StaticOrder& S, const Epi& E, const int tid) {
;     ...
;             PG8_WAIT_V(8); PG8_WAIT_L(0); PG8_BAR; PG8_MMA(0, 0, At, B0); PG8_MMA(0, 1, At, B1); PG8_BAR; PG8_SCHED;
;             PG8_LDA(At, 0, 1); PG8_STAGE(PG8_SB(0, 0), b2, voffB); PG8_STAGE(PG8_SB(0, 1), b2 + hstepB, voffB); PG8_STAGE(PG8_SA(0, 0), a2, voffA);
;             PG8_WAIT_V(8); PG8_WAIT_L(0); PG8_BAR; PG8_MMA(1, 0, At, B0); PG8_MMA(1, 1, At, B1); PG8_BAR; PG8_SCHED;
	s_setprio 1
	v_mfma_f32_16x16x32_bf16 v[124:127], v[146:149], v[202:205], v[124:127]
	v_mfma_f32_16x16x32_bf16 v[116:119], v[154:157], v[202:205], v[116:119]
	v_mfma_f32_16x16x32_bf16 v[108:111], v[146:149], v[210:213], v[108:111]
	v_mfma_f32_16x16x32_bf16 v[100:103], v[154:157], v[210:213], v[100:103]
	v_mfma_f32_16x16x32_bf16 v[92:95], v[146:149], v[226:229], v[92:95]
	v_mfma_f32_16x16x32_bf16 v[84:87], v[154:157], v[226:229], v[84:87]
	v_mfma_f32_16x16x32_bf16 v[76:79], v[146:149], v[234:237], v[76:79]
	v_mfma_f32_16x16x32_bf16 v[68:71], v[154:157], v[234:237], v[68:71]
	v_mfma_f32_16x16x32_bf16 v[124:127], v[150:153], v[206:209], v[124:127]
	v_mfma_f32_16x16x32_bf16 v[116:119], v[158:161], v[206:209], v[116:119]
	v_mfma_f32_16x16x32_bf16 v[108:111], v[150:153], v[214:217], v[108:111]
	v_mfma_f32_16x16x32_bf16 v[100:103], v[158:161], v[214:217], v[100:103]
	v_mfma_f32_16x16x32_bf16 v[92:95], v[150:153], v[230:233], v[92:95]
	v_mfma_f32_16x16x32_bf16 v[84:87], v[158:161], v[230:233], v[84:87]
	v_mfma_f32_16x16x32_bf16 v[76:79], v[150:153], v[238:241], v[76:79]
	v_mfma_f32_16x16x32_bf16 v[68:71], v[158:161], v[238:241], v[68:71]
	s_setprio 0
	s_setprio 1
	v_mfma_f32_16x16x32_bf16 v[120:123], v[162:165], v[202:205], v[120:123]
	v_mfma_f32_16x16x32_bf16 v[112:115], v[170:173], v[202:205], v[112:115]
	v_mfma_f32_16x16x32_bf16 v[104:107], v[162:165], v[210:213], v[104:107]
	v_mfma_f32_16x16x32_bf16 v[96:99], v[170:173], v[210:213], v[96:99]
	v_mfma_f32_16x16x32_bf16 v[88:91], v[162:165], v[226:229], v[88:91]
	v_mfma_f32_16x16x32_bf16 v[80:83], v[170:173], v[226:229], v[80:83]
	v_mfma_f32_16x16x32_bf16 v[72:75], v[162:165], v[234:237], v[72:75]
	v_mfma_f32_16x16x32_bf16 v[64:67], v[170:173], v[234:237], v[64:67]
	v_mfma_f32_16x16x32_bf16 v[120:123], v[166:169], v[206:209], v[120:123]
	v_mfma_f32_16x16x32_bf16 v[112:115], v[194:197], v[206:209], v[112:115]
	v_mfma_f32_16x16x32_bf16 v[104:107], v[166:169], v[214:217], v[104:107]
	v_mfma_f32_16x16x32_bf16 v[96:99], v[194:197], v[214:217], v[96:99]
	v_mfma_f32_16x16x32_bf16 v[88:91], v[166:169], v[230:233], v[88:91]
	v_mfma_f32_16x16x32_bf16 v[80:83], v[194:197], v[230:233], v[80:83]
	v_mfma_f32_16x16x32_bf16 v[72:75], v[166:169], v[238:241], v[72:75]
	v_mfma_f32_16x16x32_bf16 v[64:67], v[194:197], v[238:241], v[64:67]
	s_setprio 0
	s_barrier
	s_add_i32 s2, s56, s22
	v_lshl_add_u64 v[174:175], s[34:35], 0, v[176:177]
	s_mov_b32 m0, s2
	ds_read_b128 v[202:205], v144 offset:16384
	ds_read_b128 v[206:209], v144 offset:17408
	ds_read_b128 v[210:213], v144 offset:18432
	ds_read_b128 v[214:217], v144 offset:19456
	ds_read_b128 v[226:229], v144 offset:20480
	ds_read_b128 v[230:233], v144 offset:21504
	ds_read_b128 v[234:237], v144 offset:22528
	ds_read_b128 v[238:241], v144 offset:23552
	global_load_lds_dwordx4 v[174:175], off
	s_add_i32 m0, s2, 0x2000
	s_add_u32 s2, s34, 0x40000
	v_lshl_add_u64 v[178:179], s[34:35], 0, v[128:129]
	s_addc_u32 s3, s35, 0
	s_add_i32 s56, s57, s22
	global_load_lds_dwordx4 v[178:179], off
	v_lshl_add_u64 v[180:181], s[2:3], 0, v[176:177]
	s_mov_b32 m0, s56
	v_lshl_add_u64 v[198:199], s[40:41], 0, v[130:131]
	global_load_lds_dwordx4 v[180:181], off
	v_lshl_add_u64 v[180:181], s[2:3], 0, v[128:129]
	s_add_i32 m0, s56, 0x2000
	s_nop 0
	global_load_lds_dwordx4 v[180:181], off
	v_lshl_add_u64 v[180:181], s[40:41], 0, v[132:133]
	s_mov_b32 m0, s23
	s_nop 0
	global_load_lds_dwordx4 v[180:181], off
	s_mov_b32 m0, s30
	s_nop 0
	global_load_lds_dwordx4 v[198:199], off
	s_waitcnt vmcnt(8)
	s_waitcnt lgkmcnt(0)
	s_barrier
	s_setprio 1
	v_mfma_f32_16x16x32_bf16 v[60:63], v[146:149], v[202:205], v[60:63]
	v_mfma_f32_16x16x32_bf16 v[52:55], v[154:157], v[202:205], v[52:55]
	v_mfma_f32_16x16x32_bf16 v[44:47], v[146:149], v[210:213], v[44:47]
	v_mfma_f32_16x16x32_bf16 v[36:39], v[154:157], v[210:213], v[36:39]
	v_mfma_f32_16x16x32_bf16 v[28:31], v[146:149], v[226:229], v[28:31]
	v_mfma_f32_16x16x32_bf16 v[20:23], v[154:157], v[226:229], v[20:23]
	v_mfma_f32_16x16x32_bf16 v[12:15], v[146:149], v[234:237], v[12:15]
	v_mfma_f32_16x16x32_bf16 v[4:7], v[154:157], v[234:237], v[4:7]
	v_mfma_f32_16x16x32_bf16 v[60:63], v[150:153], v[206:209], v[60:63]
	v_mfma_f32_16x16x32_bf16 v[52:55], v[158:161], v[206:209], v[52:55]
	v_mfma_f32_16x16x32_bf16 v[44:47], v[150:153], v[214:217], v[44:47]
	v_mfma_f32_16x16x32_bf16 v[36:39], v[158:161], v[214:217], v[36:39]
	v_mfma_f32_16x16x32_bf16 v[28:31], v[150:153], v[230:233], v[28:31]
	v_mfma_f32_16x16x32_bf16 v[20:23], v[158:161], v[230:233], v[20:23]
	v_mfma_f32_16x16x32_bf16 v[12:15], v[150:153], v[238:241], v[12:15]
	v_mfma_f32_16x16x32_bf16 v[4:7], v[158:161], v[238:241], v[4:7]
	s_setprio 0
	s_setprio 1
	v_mfma_f32_16x16x32_bf16 v[56:59], v[162:165], v[202:205], v[56:59]
	v_mfma_f32_16x16x32_bf16 v[48:51], v[170:173], v[202:205], v[48:51]
	v_mfma_f32_16x16x32_bf16 v[40:43], v[162:165], v[210:213], v[40:43]
	v_mfma_f32_16x16x32_bf16 v[32:35], v[170:173], v[210:213], v[32:35]
	v_mfma_f32_16x16x32_bf16 v[24:27], v[162:165], v[226:229], v[24:27]
	v_mfma_f32_16x16x32_bf16 v[16:19], v[170:173], v[226:229], v[16:19]
	v_mfma_f32_16x16x32_bf16 v[8:11], v[162:165], v[234:237], v[8:11]
	v_mfma_f32_16x16x32_bf16 v[0:3], v[170:173], v[234:237], v[0:3]
	v_mfma_f32_16x16x32_bf16 v[56:59], v[166:169], v[206:209], v[56:59]
	v_mfma_f32_16x16x32_bf16 v[48:51], v[194:197], v[206:209], v[48:51]
	v_mfma_f32_16x16x32_bf16 v[40:43], v[166:169], v[214:217], v[40:43]
	v_mfma_f32_16x16x32_bf16 v[32:35], v[194:197], v[214:217], v[32:35]
	v_mfma_f32_16x16x32_bf16 v[24:27], v[166:169], v[230:233], v[24:27]
	v_mfma_f32_16x16x32_bf16 v[16:19], v[194:197], v[230:233], v[16:19]
	v_mfma_f32_16x16x32_bf16 v[8:11], v[166:169], v[238:241], v[8:11]
	v_mfma_f32_16x16x32_bf16 v[0:3], v[194:197], v[238:241], v[0:3]
	s_setprio 0
	s_barrier
; #define PG8_STAGE(bufoff, gbase, voff) do { _Pragma("unroll") for (int _i = 0; _i < 2; ++_i) \
;         __builtin_amdgcn_global_load_lds((const unsigned*)((const char*)(gbase) + (voff)[_i]), (LAS unsigned*)(lds + (bufoff) + ldsw + _i * 8192), 16, 0, 0); } while (0)
; #define PG8_LDA(dst, b, h) do { _Pragma("unroll") for (int m = 0; m < 4; ++m) _Pragma("unroll") for (int k = 0; k < 2; ++k) dst[m][k] = *(const LAS bf16x8*)(lds + PG8_SA(b, h) + aoff + m * 2048 + k * 1024); } while (0)
; #define PG8_LDB(dst, b, h) do { _Pragma("unroll") for (int n = 0; n < 2; ++n) _Pragma("unroll") for (int k = 0; k < 2; ++k) dst[n][k] = *(const LAS bf16x8*)(lds + PG8_SB(b, h) + boff + n * 2048 + k * 1024); } while (0)
; #define PG8_MMA(ai, bj, At, Bt) do { __builtin_amdgcn_s_setprio(1); _Pragma("unroll") for (int m = 0; m < 4; ++m) _Pragma("unroll") for (int n = 0; n < 2; ++n) _Pragma("unroll") for (int k = 0; k < 2; ++k) \
;         acc[ai][bj][m][n] = __builtin_amdgcn_mfma_f32_16x16x32_bf16(Bt[n][k], At[m][k], acc[ai][bj][m][n], 0, 0, 0); __builtin_amdgcn_s_setprio(0); } while (0)
; #define PG8_WAIT_V(n) asm volatile("s_waitcnt vmcnt(" #n ")" ::: "memory")
; #define PG8_WAIT_L(n) asm volatile("s_waitcnt lgkmcnt(" #n ")" ::: "memory")
; #define PG8_BAR __builtin_amdgcn_s_barrier()
; #define PG8_SCHED __builtin_amdgcn_sched_barrier(0)
; template <class Epi>
; __device__ __forceinline__ void gemm_phase(LAS unsigned char* lds, const Gemm g, const StaticOrder& S, const Epi& E, const int tid) {
;     ...
;             PG8_LDB(B0, 1, 0); PG8_LDB(B1, 1, 1); PG8_SCHED; PG8_LDA(At, 1, 0); PG8_STAGE(PG8_SA(0, 1), a2 + hstepA, voffA);
;             PG8_WAIT_V(8); PG8_WAIT_L(0); PG8_BAR; PG8_MMA(0, 0, At, B0); PG8_MMA(0, 1, At, B1); PG8_BAR; PG8_SCHED;
	s_add_i32 s56, 0, 0x18000
	v_add_u32_e32 v145, s56, v143
	s_add_i32 s57, 0, 0x1c000
	ds_read_b128 v[146:149], v145
	ds_read_b128 v[150:153], v145 offset:1024
	ds_read_b128 v[154:157], v145 offset:2048
	ds_read_b128 v[158:161], v145 offset:3072
	v_add_u32_e32 v145, s57, v143
	ds_read_b128 v[162:165], v145
	ds_read_b128 v[166:169], v145 offset:1024
	ds_read_b128 v[170:173], v145 offset:2048
	ds_read_b128 v[194:197], v145 offset:3072
	s_add_u32 s2, s40, 0x40000
	s_addc_u32 s3, s41, 0
	s_mov_b32 m0, s42
	v_lshl_add_u64 v[218:219], s[2:3], 0, v[132:133]
	ds_read_b128 v[202:205], v144 offset:32768
	ds_read_b128 v[206:209], v144 offset:33792
	ds_read_b128 v[210:213], v144 offset:34816
	ds_read_b128 v[214:217], v144 offset:35840
	ds_read_b128 v[226:229], v144 offset:36864
	ds_read_b128 v[230:233], v144 offset:37888
	ds_read_b128 v[234:237], v144 offset:38912
	ds_read_b128 v[238:241], v144 offset:39936
	global_load_lds_dwordx4 v[218:219], off
	v_lshl_add_u64 v[218:219], s[2:3], 0, v[130:131]
	s_mov_b32 m0, s43
	s_nop 0
	global_load_lds_dwordx4 v[218:219], off
	s_waitcnt vmcnt(8)
	s_waitcnt lgkmcnt(0)
	s_barrier
	s_setprio 1
	v_mfma_f32_16x16x32_bf16 v[124:127], v[146:149], v[202:205], v[124:127]
	v_mfma_f32_16x16x32_bf16 v[116:119], v[154:157], v[202:205], v[116:119]
	v_mfma_f32_16x16x32_bf16 v[108:111], v[146:149], v[210:213], v[108:111]
	v_mfma_f32_16x16x32_bf16 v[100:103], v[154:157], v[210:213], v[100:103]
	v_mfma_f32_16x16x32_bf16 v[92:95], v[146:149], v[226:229], v[92:95]
	v_mfma_f32_16x16x32_bf16 v[84:87], v[154:157], v[226:229], v[84:87]
	v_mfma_f32_16x16x32_bf16 v[76:79], v[146:149], v[234:237], v[76:79]
	v_mfma_f32_16x16x32_bf16 v[68:71], v[154:157], v[234:237], v[68:71]
	v_mfma_f32_16x16x32_bf16 v[124:127], v[150:153], v[206:209], v[124:127]
	v_mfma_f32_16x16x32_bf16 v[116:119], v[158:161], v[206:209], v[116:119]
	v_mfma_f32_16x16x32_bf16 v[108:111], v[150:153], v[214:217], v[108:111]
	v_mfma_f32_16x16x32_bf16 v[100:103], v[158:161], v[214:217], v[100:103]
	v_mfma_f32_16x16x32_bf16 v[92:95], v[150:153], v[230:233], v[92:95]
	v_mfma_f32_16x16x32_bf16 v[84:87], v[158:161], v[230:233], v[84:87]
	v_mfma_f32_16x16x32_bf16 v[76:79], v[150:153], v[238:241], v[76:79]
	v_mfma_f32_16x16x32_bf16 v[68:71], v[158:161], v[238:241], v[68:71]
	s_setprio 0
	s_setprio 1
	v_mfma_f32_16x16x32_bf16 v[120:123], v[162:165], v[202:205], v[120:123]
	v_mfma_f32_16x16x32_bf16 v[112:115], v[170:173], v[202:205], v[112:115]
	v_mfma_f32_16x16x32_bf16 v[104:107], v[162:165], v[210:213], v[104:107]
	v_mfma_f32_16x16x32_bf16 v[96:99], v[170:173], v[210:213], v[96:99]
	v_mfma_f32_16x16x32_bf16 v[88:91], v[162:165], v[226:229], v[88:91]
	v_mfma_f32_16x16x32_bf16 v[80:83], v[170:173], v[226:229], v[80:83]
	v_mfma_f32_16x16x32_bf16 v[72:75], v[162:165], v[234:237], v[72:75]
	v_mfma_f32_16x16x32_bf16 v[64:67], v[170:173], v[234:237], v[64:67]
	v_mfma_f32_16x16x32_bf16 v[120:123], v[166:169], v[206:209], v[120:123]
	v_mfma_f32_16x16x32_bf16 v[112:115], v[194:197], v[206:209], v[112:115]
	v_mfma_f32_16x16x32_bf16 v[104:107], v[166:169], v[214:217], v[104:107]
	v_mfma_f32_16x16x32_bf16 v[96:99], v[194:197], v[214:217], v[96:99]
	v_mfma_f32_16x16x32_bf16 v[88:91], v[166:169], v[230:233], v[88:91]
	v_mfma_f32_16x16x32_bf16 v[80:83], v[194:197], v[230:233], v[80:83]
	v_mfma_f32_16x16x32_bf16 v[72:75], v[166:169], v[238:241], v[72:75]
	v_mfma_f32_16x16x32_bf16 v[64:67], v[194:197], v[238:241], v[64:67]
	s_setprio 0
	s_barrier
; #define PG8_STAGE(bufoff, gbase, voff) do { _Pragma("unroll") for (int _i = 0; _i < 2; ++_i) \
;         __builtin_amdgcn_global_load_lds((const unsigned*)((const char*)(gbase) + (voff)[_i]), (LAS unsigned*)(lds + (bufoff) + ldsw + _i * 8192), 16, 0, 0); } while (0)
; #define PG8_LDA(dst, b, h) do { _Pragma("unroll") for (int m = 0; m < 4; ++m) _Pragma("unroll") for (int k = 0; k < 2; ++k) dst[m][k] = *(const LAS bf16x8*)(lds + PG8_SA(b, h) + aoff + m * 2048 + k * 1024); } while (0)
; #define PG8_MMA(ai, bj, At, Bt) do { __builtin_amdgcn_s_setprio(1); _Pragma("unroll") for (int m = 0; m < 4; ++m) _Pragma("unroll") for (int n = 0; n < 2; ++n) _Pragma("unroll") for (int k = 0; k < 2; ++k) \
;         acc[ai][bj][m][n] = __builtin_amdgcn_mfma_f32_16x16x32_bf16(Bt[n][k], At[m][k], acc[ai][bj][m][n], 0, 0, 0); __builtin_amdgcn_s_setprio(0); } while (0)
; #define PG8_WAIT_V(n) asm volatile("s_waitcnt vmcnt(" #n ")" ::: "memory")
; #define PG8_WAIT_L(n) asm volatile("s_waitcnt lgkmcnt(" #n ")" ::: "memory")
; #define PG8_BAR __builtin_amdgcn_s_barrier()
; #define PG8_SCHED __builtin_amdgcn_sched_barrier(0)
; template <class Epi>
; __device__ __forceinline__ void gemm_phase(LAS unsigned char* lds, const Gemm g, const StaticOrder& S, const Epi& E, const int tid) {
;     ...
;             PG8_LDA(At, 1, 1); PG8_STAGE(PG8_SB(1, 0), b3, voffB); PG8_STAGE(PG8_SB(1, 1), b3 + hstepB, voffB); PG8_STAGE(PG8_SA(1, 0), a3, voffA);
;             PG8_WAIT_V(8); PG8_WAIT_L(0); PG8_BAR; PG8_MMA(1, 0, At, B0); PG8_MMA(1, 1, At, B1); PG8_BAR; PG8_SCHED;
;         }
	s_add_i32 s2, s56, s22
	v_lshl_add_u64 v[174:175], v[174:175], 0, s[36:37]
	s_mov_b32 m0, s2
	ds_read_b128 v[202:205], v144 offset:49152
	ds_read_b128 v[206:209], v144 offset:50176
	ds_read_b128 v[210:213], v144 offset:51200
	ds_read_b128 v[214:217], v144 offset:52224
	ds_read_b128 v[226:229], v144 offset:53248
	ds_read_b128 v[230:233], v144 offset:54272
	ds_read_b128 v[234:237], v144 offset:55296
	ds_read_b128 v[238:241], v144 offset:56320
	global_load_lds_dwordx4 v[174:175], off
	s_add_i32 m0, s2, 0x2000
	s_add_u32 s2, s34, 0x40080
	v_lshl_add_u64 v[174:175], v[178:179], 0, s[36:37]
	s_addc_u32 s3, s35, 0
	s_add_i32 s34, s57, s22
	global_load_lds_dwordx4 v[174:175], off
	v_lshl_add_u64 v[174:175], s[2:3], 0, v[176:177]
	s_mov_b32 m0, s34
	s_nop 0
	global_load_lds_dwordx4 v[174:175], off
	v_lshl_add_u64 v[174:175], s[2:3], 0, v[128:129]
	s_add_i32 m0, s34, 0x2000
	s_nop 0
	global_load_lds_dwordx4 v[174:175], off
	v_lshl_add_u64 v[174:175], v[180:181], 0, s[76:77]
	s_mov_b32 m0, s45
	s_nop 0
	global_load_lds_dwordx4 v[174:175], off
	v_lshl_add_u64 v[174:175], v[198:199], 0, s[76:77]
	s_mov_b32 m0, s46
	s_nop 0
	global_load_lds_dwordx4 v[174:175], off
	s_waitcnt vmcnt(8)
	s_waitcnt lgkmcnt(0)
	s_barrier
	s_setprio 1
	v_mfma_f32_16x16x32_bf16 v[60:63], v[146:149], v[202:205], v[60:63]
	v_mfma_f32_16x16x32_bf16 v[52:55], v[154:157], v[202:205], v[52:55]
	v_mfma_f32_16x16x32_bf16 v[44:47], v[146:149], v[210:213], v[44:47]
	v_mfma_f32_16x16x32_bf16 v[36:39], v[154:157], v[210:213], v[36:39]
	v_mfma_f32_16x16x32_bf16 v[28:31], v[146:149], v[226:229], v[28:31]
	v_mfma_f32_16x16x32_bf16 v[20:23], v[154:157], v[226:229], v[20:23]
	v_mfma_f32_16x16x32_bf16 v[12:15], v[146:149], v[234:237], v[12:15]
	v_mfma_f32_16x16x32_bf16 v[4:7], v[154:157], v[234:237], v[4:7]
	v_mfma_f32_16x16x32_bf16 v[60:63], v[150:153], v[206:209], v[60:63]
	v_mfma_f32_16x16x32_bf16 v[52:55], v[158:161], v[206:209], v[52:55]
	v_mfma_f32_16x16x32_bf16 v[44:47], v[150:153], v[214:217], v[44:47]
	v_mfma_f32_16x16x32_bf16 v[36:39], v[158:161], v[214:217], v[36:39]
	v_mfma_f32_16x16x32_bf16 v[28:31], v[150:153], v[230:233], v[28:31]
	v_mfma_f32_16x16x32_bf16 v[20:23], v[158:161], v[230:233], v[20:23]
	v_mfma_f32_16x16x32_bf16 v[12:15], v[150:153], v[238:241], v[12:15]
	v_mfma_f32_16x16x32_bf16 v[4:7], v[158:161], v[238:241], v[4:7]
	s_setprio 0
	s_setprio 1
	v_mfma_f32_16x16x32_bf16 v[56:59], v[162:165], v[202:205], v[56:59]
	v_mfma_f32_16x16x32_bf16 v[48:51], v[170:173], v[202:205], v[48:51]
	v_mfma_f32_16x16x32_bf16 v[40:43], v[162:165], v[210:213], v[40:43]
	v_mfma_f32_16x16x32_bf16 v[32:35], v[170:173], v[210:213], v[32:35]
	v_mfma_f32_16x16x32_bf16 v[24:27], v[162:165], v[226:229], v[24:27]
	v_mfma_f32_16x16x32_bf16 v[16:19], v[170:173], v[226:229], v[16:19]
	v_mfma_f32_16x16x32_bf16 v[8:11], v[162:165], v[234:237], v[8:11]
	v_mfma_f32_16x16x32_bf16 v[0:3], v[170:173], v[234:237], v[0:3]
	v_mfma_f32_16x16x32_bf16 v[56:59], v[166:169], v[206:209], v[56:59]
	v_mfma_f32_16x16x32_bf16 v[48:51], v[194:197], v[206:209], v[48:51]
	v_mfma_f32_16x16x32_bf16 v[40:43], v[166:169], v[214:217], v[40:43]
	v_mfma_f32_16x16x32_bf16 v[32:35], v[194:197], v[214:217], v[32:35]
	v_mfma_f32_16x16x32_bf16 v[24:27], v[166:169], v[230:233], v[24:27]
	v_mfma_f32_16x16x32_bf16 v[16:19], v[194:197], v[230:233], v[16:19]
	v_mfma_f32_16x16x32_bf16 v[8:11], v[166:169], v[238:241], v[8:11]
	v_mfma_f32_16x16x32_bf16 v[0:3], v[194:197], v[238:241], v[0:3]
	s_setprio 0
	s_barrier
	s_add_i32 s55, s55, 2
	s_add_u32 s53, s53, 0x100
	s_addc_u32 s54, s54, 0
	s_cmp_gt_u32 s55, 13
	s_mov_b64 s[2:3], s[28:29]
	s_cbranch_scc0 .LBB0_453
	s_and_b64 vcc, exec, s[8:9]
	s_cbranch_vccz .LBB0_456
	s_barrier
